# kv-up k-rows copy-out loads issued up front for both unrolled bodies + s_setprio 1 around MFMA runs in 8x4 main loops
# speedup vs baseline: 1.0154x; 1.0154x over previous
; #define LDB_(dst, ks) _Pragma("unroll") for (int n = 0; n < 4; ++n) dst[n] = *(const bf16x8*)(sB + b_off + n * 2048 + (ks) * 1024)
; #define LDA_(dst, ks, h) _Pragma("unroll") for (int m = 0; m < 4; ++m) dst[m] = *(const bf16x8*)(sA + a_off + ((h) * 4 + m) * 2048 + (ks) * 1024)
; #define MMA_(A, B, h) _Pragma("unroll") for (int m = 0; m < 4; ++m) _Pragma("unroll") for (int n = 0; n < 4; ++n) \
;       acc[(h) * 4 + m][n] = SWAP ? MFMA16(B[n], A[m], acc[(h) * 4 + m][n]) : MFMA16(A[m], B[n], acc[(h) * 4 + m][n])
; template <int MF, int NF, bool SWAP = true>
; DI void gemm_main(f32x4 (&acc)[MF][NF], const u16* __restrict__ Ab, int lda, const u16* __restrict__ Bb, int ldb,
;                   int K, char* shm) {
;     ...
;     if constexpr (MF == 8 && NF == 4) {
;       bf16x8 B0[4], B1[4], A0[4], A1[4], A2[4], A3[4];
;     ...
;       LDB_(B0, 0); LDA_(A0, 0, 0);
;       LDA_(A1, 0, 1); MMA_(A0, B0, 0);
;       LDB_(B1, 1); LDA_(A2, 1, 0); MMA_(A1, B0, 1);
;       LDA_(A3, 1, 1); MMA_(A2, B1, 0);
;       MMA_(A3, B1, 1);
;     ...
;       __builtin_amdgcn_sched_group_barrier(0x100, 8, 0);
; #pragma unroll
;       for (int i = 0; i < 4; ++i) { __builtin_amdgcn_sched_group_barrier(0x100, 1, 0); __builtin_amdgcn_sched_group_barrier(0x008, 4, 0); }
; #pragma unroll
;       for (int i = 0; i < 8; ++i) { __builtin_amdgcn_sched_group_barrier(0x100, 1, 0); __builtin_amdgcn_sched_group_barrier(0x008, 2, 0); }
; #pragma unroll
;       for (int i = 0; i < 4; ++i) { __builtin_amdgcn_sched_group_barrier(0x100, 1, 0); __builtin_amdgcn_sched_group_barrier(0x008, 4, 0); }
;       __builtin_amdgcn_sched_group_barrier(0x008, 16, 0);
;       __builtin_amdgcn_sched_barrier(0);
;     ...
;     if constexpr (RING3) {
;       if (t + 2 < nt) asm volatile("s_waitcnt vmcnt(6)" ::: "memory");
;       else asm volatile("s_waitcnt vmcnt(0)" ::: "memory");
;       asm volatile("s_waitcnt lgkmcnt(0)" ::: "memory");
;       __builtin_amdgcn_s_barrier();
;       cur3 = (cur3 == 2) ? 0 : cur3 + 1;
;       nxt3 = (nxt3 == 2) ? 0 : nxt3 + 1;
;     } else {
;       asm volatile("s_waitcnt vmcnt(0)" ::: "memory");
;       __syncthreads();
;     }
.Lg_rot146_main:
	s_waitcnt lgkmcnt(4)
	s_setprio 1
	v_mfma_f32_16x16x32_bf16 v[124:127], v[138:141], v[154:157], v[124:127]
	v_mfma_f32_16x16x32_bf16 v[120:123], v[142:145], v[154:157], v[120:123]
	v_mfma_f32_16x16x32_bf16 v[116:119], v[146:149], v[154:157], v[116:119]
	v_mfma_f32_16x16x32_bf16 v[112:115], v[150:153], v[154:157], v[112:115]
	s_setprio 0
	ds_read_b128 v[154:157], v137 offset:10240
	s_waitcnt lgkmcnt(4)
	s_setprio 1
	v_mfma_f32_16x16x32_bf16 v[108:111], v[138:141], v[158:161], v[108:111]
	v_mfma_f32_16x16x32_bf16 v[104:107], v[142:145], v[158:161], v[104:107]
	v_mfma_f32_16x16x32_bf16 v[100:103], v[146:149], v[158:161], v[100:103]
	v_mfma_f32_16x16x32_bf16 v[96:99], v[150:153], v[158:161], v[96:99]
	s_setprio 0
	ds_read_b128 v[158:161], v137 offset:12288
	s_waitcnt lgkmcnt(4)
	s_setprio 1
	v_mfma_f32_16x16x32_bf16 v[92:95], v[138:141], v[162:165], v[92:95]
	v_mfma_f32_16x16x32_bf16 v[88:91], v[142:145], v[162:165], v[88:91]
	v_mfma_f32_16x16x32_bf16 v[84:87], v[146:149], v[162:165], v[84:87]
	v_mfma_f32_16x16x32_bf16 v[80:83], v[150:153], v[162:165], v[80:83]
	s_setprio 0
	ds_read_b128 v[162:165], v137 offset:14336
	s_waitcnt lgkmcnt(4)
	s_setprio 1
	v_mfma_f32_16x16x32_bf16 v[76:79], v[138:141], v[166:169], v[76:79]
	v_mfma_f32_16x16x32_bf16 v[72:75], v[142:145], v[166:169], v[72:75]
	v_mfma_f32_16x16x32_bf16 v[68:71], v[146:149], v[166:169], v[68:71]
	v_mfma_f32_16x16x32_bf16 v[64:67], v[150:153], v[166:169], v[64:67]
	s_setprio 0
	ds_read_b128 v[186:189], v178 offset:33792
	s_waitcnt lgkmcnt(4)
	s_setprio 1
	v_mfma_f32_16x16x32_bf16 v[60:63], v[138:141], v[170:173], v[60:63]
	v_mfma_f32_16x16x32_bf16 v[56:59], v[142:145], v[170:173], v[56:59]
	s_setprio 0
	ds_read_b128 v[194:197], v178 offset:35840
	s_setprio 1
	v_mfma_f32_16x16x32_bf16 v[52:55], v[146:149], v[170:173], v[52:55]
	v_mfma_f32_16x16x32_bf16 v[48:51], v[150:153], v[170:173], v[48:51]
	s_setprio 0
	ds_read_b128 v[198:201], v178 offset:37888
	s_waitcnt lgkmcnt(5)
	s_setprio 1
	v_mfma_f32_16x16x32_bf16 v[44:47], v[138:141], v[154:157], v[44:47]
	v_mfma_f32_16x16x32_bf16 v[40:43], v[142:145], v[154:157], v[40:43]
	s_setprio 0
	ds_read_b128 v[212:215], v178 offset:39936
	s_setprio 1
	v_mfma_f32_16x16x32_bf16 v[36:39], v[146:149], v[154:157], v[36:39]
	v_mfma_f32_16x16x32_bf16 v[32:35], v[150:153], v[154:157], v[32:35]
	s_setprio 0
	ds_read_b128 v[154:157], v137 offset:1024
	s_waitcnt lgkmcnt(6)
	s_setprio 1
	v_mfma_f32_16x16x32_bf16 v[28:31], v[138:141], v[158:161], v[28:31]
	v_mfma_f32_16x16x32_bf16 v[24:27], v[142:145], v[158:161], v[24:27]
	s_setprio 0
	ds_read_b128 v[182:185], v137 offset:3072
	s_setprio 1
	v_mfma_f32_16x16x32_bf16 v[20:23], v[146:149], v[158:161], v[20:23]
	v_mfma_f32_16x16x32_bf16 v[16:19], v[150:153], v[158:161], v[16:19]
	s_setprio 0
	ds_read_b128 v[158:161], v137 offset:5120
	s_waitcnt lgkmcnt(7)
	s_setprio 1
	v_mfma_f32_16x16x32_bf16 v[12:15], v[138:141], v[162:165], v[12:15]
	v_mfma_f32_16x16x32_bf16 v[8:11], v[142:145], v[162:165], v[8:11]
	s_setprio 0
	ds_read_b128 v[138:141], v137 offset:7168
	s_setprio 1
	v_mfma_f32_16x16x32_bf16 v[4:7], v[146:149], v[162:165], v[4:7]
	v_mfma_f32_16x16x32_bf16 v[0:3], v[150:153], v[162:165], v[0:3]
	s_setprio 0
	ds_read_b128 v[190:193], v137 offset:9216
	s_waitcnt lgkmcnt(4)
	s_setprio 1
	v_mfma_f32_16x16x32_bf16 v[124:127], v[186:189], v[154:157], v[124:127]
	v_mfma_f32_16x16x32_bf16 v[120:123], v[194:197], v[154:157], v[120:123]
	v_mfma_f32_16x16x32_bf16 v[116:119], v[198:201], v[154:157], v[116:119]
	v_mfma_f32_16x16x32_bf16 v[112:115], v[212:215], v[154:157], v[112:115]
	s_setprio 0
	ds_read_b128 v[216:219], v137 offset:11264
	s_waitcnt lgkmcnt(4)
	s_setprio 1
	v_mfma_f32_16x16x32_bf16 v[108:111], v[186:189], v[182:185], v[108:111]
	v_mfma_f32_16x16x32_bf16 v[104:107], v[194:197], v[182:185], v[104:107]
	v_mfma_f32_16x16x32_bf16 v[100:103], v[198:201], v[182:185], v[100:103]
	v_mfma_f32_16x16x32_bf16 v[96:99], v[212:215], v[182:185], v[96:99]
	s_setprio 0
	ds_read_b128 v[220:223], v137 offset:13312
	s_waitcnt lgkmcnt(4)
	s_setprio 1
	v_mfma_f32_16x16x32_bf16 v[92:95], v[186:189], v[158:161], v[92:95]
	v_mfma_f32_16x16x32_bf16 v[88:91], v[194:197], v[158:161], v[88:91]
	v_mfma_f32_16x16x32_bf16 v[84:87], v[198:201], v[158:161], v[84:87]
	v_mfma_f32_16x16x32_bf16 v[80:83], v[212:215], v[158:161], v[80:83]
	s_setprio 0
	ds_read_b128 v[224:227], v137 offset:15360
	s_waitcnt lgkmcnt(4)
	s_setprio 1
	v_mfma_f32_16x16x32_bf16 v[76:79], v[186:189], v[138:141], v[76:79]
	v_mfma_f32_16x16x32_bf16 v[72:75], v[194:197], v[138:141], v[72:75]
	v_mfma_f32_16x16x32_bf16 v[68:71], v[198:201], v[138:141], v[68:71]
	v_mfma_f32_16x16x32_bf16 v[64:67], v[212:215], v[138:141], v[64:67]
	s_waitcnt lgkmcnt(0)
	s_setprio 0
	s_waitcnt vmcnt(0)
	s_add_i32 s11, s11, 64
	s_add_i32 s17, s17, 0x10000
	s_add_i32 s13, s13, 1
	s_cmpk_lg_i32 s11, 0x400
	s_waitcnt vmcnt(0)
	s_barrier
	s_cbranch_scc1 .LBB0_146
	v_mfma_f32_16x16x32_bf16 v[60:63], v[186:189], v[190:193], v[60:63]
	v_mfma_f32_16x16x32_bf16 v[56:59], v[194:197], v[190:193], v[56:59]
	v_mfma_f32_16x16x32_bf16 v[52:55], v[198:201], v[190:193], v[52:55]
	v_mfma_f32_16x16x32_bf16 v[48:51], v[212:215], v[190:193], v[48:51]
	v_mfma_f32_16x16x32_bf16 v[44:47], v[186:189], v[216:219], v[44:47]
	v_mfma_f32_16x16x32_bf16 v[40:43], v[194:197], v[216:219], v[40:43]
	v_mfma_f32_16x16x32_bf16 v[36:39], v[198:201], v[216:219], v[36:39]
	v_mfma_f32_16x16x32_bf16 v[32:35], v[212:215], v[216:219], v[32:35]
	v_mfma_f32_16x16x32_bf16 v[28:31], v[186:189], v[220:223], v[28:31]
	v_mfma_f32_16x16x32_bf16 v[24:27], v[194:197], v[220:223], v[24:27]
	v_mfma_f32_16x16x32_bf16 v[20:23], v[198:201], v[220:223], v[20:23]
	v_mfma_f32_16x16x32_bf16 v[16:19], v[212:215], v[220:223], v[16:19]
	v_mfma_f32_16x16x32_bf16 v[12:15], v[186:189], v[224:227], v[12:15]
	v_mfma_f32_16x16x32_bf16 v[8:11], v[194:197], v[224:227], v[8:11]
	v_mfma_f32_16x16x32_bf16 v[4:7], v[198:201], v[224:227], v[4:7]
	v_mfma_f32_16x16x32_bf16 v[0:3], v[212:215], v[224:227], v[0:3]
	s_nop 7
	s_nop 1

; #define LDB_(dst, ks) _Pragma("unroll") for (int n = 0; n < 4; ++n) dst[n] = *(const bf16x8*)(sB + b_off + n * 2048 + (ks) * 1024)
; #define LDA_(dst, ks, h) _Pragma("unroll") for (int m = 0; m < 4; ++m) dst[m] = *(const bf16x8*)(sA + a_off + ((h) * 4 + m) * 2048 + (ks) * 1024)
; #define MMA_(A, B, h) _Pragma("unroll") for (int m = 0; m < 4; ++m) _Pragma("unroll") for (int n = 0; n < 4; ++n) \
;       acc[(h) * 4 + m][n] = SWAP ? MFMA16(B[n], A[m], acc[(h) * 4 + m][n]) : MFMA16(A[m], B[n], acc[(h) * 4 + m][n])
; template <int MF, int NF, bool SWAP = true>
; DI void gemm_main(f32x4 (&acc)[MF][NF], const u16* __restrict__ Ab, int lda, const u16* __restrict__ Bb, int ldb,
;                   int K, char* shm) {
;     ...
;     if constexpr (MF == 8 && NF == 4) {
;       bf16x8 B0[4], B1[4], A0[4], A1[4], A2[4], A3[4];
;     ...
;       LDB_(B0, 0); LDA_(A0, 0, 0);
;       LDA_(A1, 0, 1); MMA_(A0, B0, 0);
;       LDB_(B1, 1); LDA_(A2, 1, 0); MMA_(A1, B0, 1);
;       LDA_(A3, 1, 1); MMA_(A2, B1, 0);
;       MMA_(A3, B1, 1);
;     ...
;       __builtin_amdgcn_sched_group_barrier(0x100, 8, 0);
; #pragma unroll
;       for (int i = 0; i < 4; ++i) { __builtin_amdgcn_sched_group_barrier(0x100, 1, 0); __builtin_amdgcn_sched_group_barrier(0x008, 4, 0); }
; #pragma unroll
;       for (int i = 0; i < 8; ++i) { __builtin_amdgcn_sched_group_barrier(0x100, 1, 0); __builtin_amdgcn_sched_group_barrier(0x008, 2, 0); }
; #pragma unroll
;       for (int i = 0; i < 4; ++i) { __builtin_amdgcn_sched_group_barrier(0x100, 1, 0); __builtin_amdgcn_sched_group_barrier(0x008, 4, 0); }
;       __builtin_amdgcn_sched_group_barrier(0x008, 16, 0);
;       __builtin_amdgcn_sched_barrier(0);
;     ...
;     if constexpr (RING3) {
;       if (t + 2 < nt) asm volatile("s_waitcnt vmcnt(6)" ::: "memory");
;       else asm volatile("s_waitcnt vmcnt(0)" ::: "memory");
;       asm volatile("s_waitcnt lgkmcnt(0)" ::: "memory");
;       __builtin_amdgcn_s_barrier();
;       cur3 = (cur3 == 2) ? 0 : cur3 + 1;
;       nxt3 = (nxt3 == 2) ? 0 : nxt3 + 1;
;     } else {
;       asm volatile("s_waitcnt vmcnt(0)" ::: "memory");
;       __syncthreads();
;     }
.Lg_rot244_main:
	s_waitcnt lgkmcnt(4)
	s_setprio 1
	v_mfma_f32_16x16x32_bf16 v[124:127], v[138:141], v[154:157], v[124:127]
	v_mfma_f32_16x16x32_bf16 v[120:123], v[142:145], v[154:157], v[120:123]
	v_mfma_f32_16x16x32_bf16 v[116:119], v[146:149], v[154:157], v[116:119]
	v_mfma_f32_16x16x32_bf16 v[112:115], v[150:153], v[154:157], v[112:115]
	s_setprio 0
	ds_read_b128 v[154:157], v186 offset:10240
	s_waitcnt lgkmcnt(4)
	s_setprio 1
	v_mfma_f32_16x16x32_bf16 v[108:111], v[138:141], v[158:161], v[108:111]
	v_mfma_f32_16x16x32_bf16 v[104:107], v[142:145], v[158:161], v[104:107]
	v_mfma_f32_16x16x32_bf16 v[100:103], v[146:149], v[158:161], v[100:103]
	v_mfma_f32_16x16x32_bf16 v[96:99], v[150:153], v[158:161], v[96:99]
	s_setprio 0
	ds_read_b128 v[158:161], v186 offset:12288
	s_waitcnt lgkmcnt(4)
	s_setprio 1
	v_mfma_f32_16x16x32_bf16 v[92:95], v[138:141], v[162:165], v[92:95]
	v_mfma_f32_16x16x32_bf16 v[88:91], v[142:145], v[162:165], v[88:91]
	v_mfma_f32_16x16x32_bf16 v[84:87], v[146:149], v[162:165], v[84:87]
	v_mfma_f32_16x16x32_bf16 v[80:83], v[150:153], v[162:165], v[80:83]
	s_setprio 0
	ds_read_b128 v[162:165], v186 offset:14336
	s_waitcnt lgkmcnt(4)
	s_setprio 1
	v_mfma_f32_16x16x32_bf16 v[76:79], v[138:141], v[166:169], v[76:79]
	v_mfma_f32_16x16x32_bf16 v[72:75], v[142:145], v[166:169], v[72:75]
	v_mfma_f32_16x16x32_bf16 v[68:71], v[146:149], v[166:169], v[68:71]
	v_mfma_f32_16x16x32_bf16 v[64:67], v[150:153], v[166:169], v[64:67]
	s_setprio 0
	ds_read_b128 v[188:191], v178 offset:33792
	s_waitcnt lgkmcnt(4)
	s_setprio 1
	v_mfma_f32_16x16x32_bf16 v[60:63], v[138:141], v[170:173], v[60:63]
	v_mfma_f32_16x16x32_bf16 v[56:59], v[142:145], v[170:173], v[56:59]
	s_setprio 0
	ds_read_b128 v[196:199], v178 offset:35840
	s_setprio 1
	v_mfma_f32_16x16x32_bf16 v[52:55], v[146:149], v[170:173], v[52:55]
	v_mfma_f32_16x16x32_bf16 v[48:51], v[150:153], v[170:173], v[48:51]
	s_setprio 0
	ds_read_b128 v[212:215], v178 offset:37888
	s_waitcnt lgkmcnt(5)
	s_setprio 1
	v_mfma_f32_16x16x32_bf16 v[44:47], v[138:141], v[154:157], v[44:47]
	v_mfma_f32_16x16x32_bf16 v[40:43], v[142:145], v[154:157], v[40:43]
	s_setprio 0
	ds_read_b128 v[216:219], v178 offset:39936
	s_setprio 1
	v_mfma_f32_16x16x32_bf16 v[36:39], v[146:149], v[154:157], v[36:39]
	v_mfma_f32_16x16x32_bf16 v[32:35], v[150:153], v[154:157], v[32:35]
	s_setprio 0
	ds_read_b128 v[154:157], v186 offset:1024
	s_waitcnt lgkmcnt(6)
	s_setprio 1
	v_mfma_f32_16x16x32_bf16 v[28:31], v[138:141], v[158:161], v[28:31]
	v_mfma_f32_16x16x32_bf16 v[24:27], v[142:145], v[158:161], v[24:27]
	s_setprio 0
	ds_read_b128 v[182:185], v186 offset:3072
	s_setprio 1
	v_mfma_f32_16x16x32_bf16 v[20:23], v[146:149], v[158:161], v[20:23]
	v_mfma_f32_16x16x32_bf16 v[16:19], v[150:153], v[158:161], v[16:19]
	s_setprio 0
	ds_read_b128 v[158:161], v186 offset:5120
	s_waitcnt lgkmcnt(7)
	s_setprio 1
	v_mfma_f32_16x16x32_bf16 v[12:15], v[138:141], v[162:165], v[12:15]
	v_mfma_f32_16x16x32_bf16 v[8:11], v[142:145], v[162:165], v[8:11]
	s_setprio 0
	ds_read_b128 v[138:141], v186 offset:7168
	s_setprio 1
	v_mfma_f32_16x16x32_bf16 v[4:7], v[146:149], v[162:165], v[4:7]
	v_mfma_f32_16x16x32_bf16 v[0:3], v[150:153], v[162:165], v[0:3]
	s_setprio 0
	ds_read_b128 v[192:195], v186 offset:9216
	s_waitcnt lgkmcnt(4)
	s_setprio 1
	v_mfma_f32_16x16x32_bf16 v[124:127], v[188:191], v[154:157], v[124:127]
	v_mfma_f32_16x16x32_bf16 v[120:123], v[196:199], v[154:157], v[120:123]
	v_mfma_f32_16x16x32_bf16 v[116:119], v[212:215], v[154:157], v[116:119]
	v_mfma_f32_16x16x32_bf16 v[112:115], v[216:219], v[154:157], v[112:115]
	s_setprio 0
	ds_read_b128 v[220:223], v186 offset:11264
	s_waitcnt lgkmcnt(4)
	s_setprio 1
	v_mfma_f32_16x16x32_bf16 v[108:111], v[188:191], v[182:185], v[108:111]
	v_mfma_f32_16x16x32_bf16 v[104:107], v[196:199], v[182:185], v[104:107]
	v_mfma_f32_16x16x32_bf16 v[100:103], v[212:215], v[182:185], v[100:103]
	v_mfma_f32_16x16x32_bf16 v[96:99], v[216:219], v[182:185], v[96:99]
	s_setprio 0
	ds_read_b128 v[224:227], v186 offset:13312
	s_waitcnt lgkmcnt(4)
	s_setprio 1
	v_mfma_f32_16x16x32_bf16 v[92:95], v[188:191], v[158:161], v[92:95]
	v_mfma_f32_16x16x32_bf16 v[88:91], v[196:199], v[158:161], v[88:91]
	v_mfma_f32_16x16x32_bf16 v[84:87], v[212:215], v[158:161], v[84:87]
	v_mfma_f32_16x16x32_bf16 v[80:83], v[216:219], v[158:161], v[80:83]
	s_setprio 0
	ds_read_b128 v[228:231], v186 offset:15360
	s_waitcnt lgkmcnt(4)
	s_setprio 1
	v_mfma_f32_16x16x32_bf16 v[76:79], v[188:191], v[138:141], v[76:79]
	v_mfma_f32_16x16x32_bf16 v[72:75], v[196:199], v[138:141], v[72:75]
	v_mfma_f32_16x16x32_bf16 v[68:71], v[212:215], v[138:141], v[68:71]
	v_mfma_f32_16x16x32_bf16 v[64:67], v[216:219], v[138:141], v[64:67]
	s_waitcnt lgkmcnt(0)
	s_setprio 0
	s_waitcnt vmcnt(0)
	s_add_i32 s16, s16, 64
	s_add_i32 s15, s15, 0x10000
	s_add_i32 s17, s17, 1
	s_cmpk_lg_i32 s16, 0x400
	s_waitcnt vmcnt(0)
	s_barrier
	s_cbranch_scc1 .LBB0_244
	v_mfma_f32_16x16x32_bf16 v[60:63], v[188:191], v[192:195], v[60:63]
	v_mfma_f32_16x16x32_bf16 v[56:59], v[196:199], v[192:195], v[56:59]
	v_mfma_f32_16x16x32_bf16 v[52:55], v[212:215], v[192:195], v[52:55]
	v_mfma_f32_16x16x32_bf16 v[48:51], v[216:219], v[192:195], v[48:51]
	v_mfma_f32_16x16x32_bf16 v[44:47], v[188:191], v[220:223], v[44:47]
	v_mfma_f32_16x16x32_bf16 v[40:43], v[196:199], v[220:223], v[40:43]
	v_mfma_f32_16x16x32_bf16 v[36:39], v[212:215], v[220:223], v[36:39]
	v_mfma_f32_16x16x32_bf16 v[32:35], v[216:219], v[220:223], v[32:35]
	v_mfma_f32_16x16x32_bf16 v[28:31], v[188:191], v[224:227], v[28:31]
	v_mfma_f32_16x16x32_bf16 v[24:27], v[196:199], v[224:227], v[24:27]
	v_mfma_f32_16x16x32_bf16 v[20:23], v[212:215], v[224:227], v[20:23]
	v_mfma_f32_16x16x32_bf16 v[16:19], v[216:219], v[224:227], v[16:19]
	v_mfma_f32_16x16x32_bf16 v[12:15], v[188:191], v[228:231], v[12:15]
	v_mfma_f32_16x16x32_bf16 v[8:11], v[196:199], v[228:231], v[8:11]
	v_mfma_f32_16x16x32_bf16 v[4:7], v[212:215], v[228:231], v[4:7]
	v_mfma_f32_16x16x32_bf16 v[0:3], v[216:219], v[228:231], v[0:3]
	s_nop 7
	s_nop 1

; #define LDB_(dst, ks) _Pragma("unroll") for (int n = 0; n < 4; ++n) dst[n] = *(const bf16x8*)(sB + b_off + n * 2048 + (ks) * 1024)
; #define LDA_(dst, ks, h) _Pragma("unroll") for (int m = 0; m < 4; ++m) dst[m] = *(const bf16x8*)(sA + a_off + ((h) * 4 + m) * 2048 + (ks) * 1024)
; #define MMA_(A, B, h) _Pragma("unroll") for (int m = 0; m < 4; ++m) _Pragma("unroll") for (int n = 0; n < 4; ++n) \
;       acc[(h) * 4 + m][n] = SWAP ? MFMA16(B[n], A[m], acc[(h) * 4 + m][n]) : MFMA16(A[m], B[n], acc[(h) * 4 + m][n])
; template <int MF, int NF, bool SWAP = true>
; DI void gemm_main(f32x4 (&acc)[MF][NF], const u16* __restrict__ Ab, int lda, const u16* __restrict__ Bb, int ldb,
;                   int K, char* shm) {
;     ...
;     if constexpr (MF == 8 && NF == 4) {
;       bf16x8 B0[4], B1[4], A0[4], A1[4], A2[4], A3[4];
;     ...
;       LDB_(B0, 0); LDA_(A0, 0, 0);
;       LDA_(A1, 0, 1); MMA_(A0, B0, 0);
;       LDB_(B1, 1); LDA_(A2, 1, 0); MMA_(A1, B0, 1);
;       LDA_(A3, 1, 1); MMA_(A2, B1, 0);
;       MMA_(A3, B1, 1);
;     ...
;       __builtin_amdgcn_sched_group_barrier(0x100, 8, 0);
; #pragma unroll
;       for (int i = 0; i < 4; ++i) { __builtin_amdgcn_sched_group_barrier(0x100, 1, 0); __builtin_amdgcn_sched_group_barrier(0x008, 4, 0); }
; #pragma unroll
;       for (int i = 0; i < 8; ++i) { __builtin_amdgcn_sched_group_barrier(0x100, 1, 0); __builtin_amdgcn_sched_group_barrier(0x008, 2, 0); }
; #pragma unroll
;       for (int i = 0; i < 4; ++i) { __builtin_amdgcn_sched_group_barrier(0x100, 1, 0); __builtin_amdgcn_sched_group_barrier(0x008, 4, 0); }
;       __builtin_amdgcn_sched_group_barrier(0x008, 16, 0);
;       __builtin_amdgcn_sched_barrier(0);
;     ...
;     if constexpr (RING3) {
;       if (t + 2 < nt) asm volatile("s_waitcnt vmcnt(6)" ::: "memory");
;       else asm volatile("s_waitcnt vmcnt(0)" ::: "memory");
;       asm volatile("s_waitcnt lgkmcnt(0)" ::: "memory");
;       __builtin_amdgcn_s_barrier();
;       cur3 = (cur3 == 2) ? 0 : cur3 + 1;
;       nxt3 = (nxt3 == 2) ? 0 : nxt3 + 1;
;     } else {
;       asm volatile("s_waitcnt vmcnt(0)" ::: "memory");
;       __syncthreads();
;     }
.Lg_rot314_main:
	s_waitcnt lgkmcnt(6)
	s_setprio 1
	v_mfma_f32_16x16x32_bf16 v[124:127], v[138:141], v[142:145], v[124:127]
	s_waitcnt lgkmcnt(5)
	v_mfma_f32_16x16x32_bf16 v[120:123], v[138:141], v[146:149], v[120:123]
	s_waitcnt lgkmcnt(4)
	v_mfma_f32_16x16x32_bf16 v[116:119], v[138:141], v[150:153], v[116:119]
	s_waitcnt lgkmcnt(3)
	v_mfma_f32_16x16x32_bf16 v[112:115], v[138:141], v[154:157], v[112:115]
	s_setprio 0
	ds_read_b128 v[138:141], v186 offset:10240
	s_setprio 1
	v_mfma_f32_16x16x32_bf16 v[108:111], v[158:161], v[142:145], v[108:111]
	v_mfma_f32_16x16x32_bf16 v[104:107], v[158:161], v[146:149], v[104:107]
	v_mfma_f32_16x16x32_bf16 v[100:103], v[158:161], v[150:153], v[100:103]
	v_mfma_f32_16x16x32_bf16 v[96:99], v[158:161], v[154:157], v[96:99]
	s_setprio 0
	ds_read_b128 v[158:161], v186 offset:12288
	s_waitcnt lgkmcnt(4)
	s_setprio 1
	v_mfma_f32_16x16x32_bf16 v[92:95], v[162:165], v[142:145], v[92:95]
	v_mfma_f32_16x16x32_bf16 v[88:91], v[162:165], v[146:149], v[88:91]
	v_mfma_f32_16x16x32_bf16 v[84:87], v[162:165], v[150:153], v[84:87]
	v_mfma_f32_16x16x32_bf16 v[80:83], v[162:165], v[154:157], v[80:83]
	s_setprio 0
	ds_read_b128 v[162:165], v186 offset:14336
	s_waitcnt lgkmcnt(4)
	s_setprio 1
	v_mfma_f32_16x16x32_bf16 v[76:79], v[166:169], v[142:145], v[76:79]
	v_mfma_f32_16x16x32_bf16 v[72:75], v[166:169], v[146:149], v[72:75]
	v_mfma_f32_16x16x32_bf16 v[68:71], v[166:169], v[150:153], v[68:71]
	v_mfma_f32_16x16x32_bf16 v[64:67], v[166:169], v[154:157], v[64:67]
	s_setprio 0
	ds_read_b128 v[192:195], v178 offset:33792
	s_waitcnt lgkmcnt(4)
	s_setprio 1
	v_mfma_f32_16x16x32_bf16 v[60:63], v[170:173], v[142:145], v[60:63]
	v_mfma_f32_16x16x32_bf16 v[56:59], v[170:173], v[146:149], v[56:59]
	s_setprio 0
	ds_read_b128 v[196:199], v178 offset:35840
	s_setprio 1
	v_mfma_f32_16x16x32_bf16 v[52:55], v[170:173], v[150:153], v[52:55]
	v_mfma_f32_16x16x32_bf16 v[48:51], v[170:173], v[154:157], v[48:51]
	s_setprio 0
	ds_read_b128 v[212:215], v178 offset:37888
	s_waitcnt lgkmcnt(5)
	s_setprio 1
	v_mfma_f32_16x16x32_bf16 v[44:47], v[138:141], v[142:145], v[44:47]
	v_mfma_f32_16x16x32_bf16 v[40:43], v[138:141], v[146:149], v[40:43]
	s_setprio 0
	ds_read_b128 v[216:219], v178 offset:39936
	s_setprio 1
	v_mfma_f32_16x16x32_bf16 v[36:39], v[138:141], v[150:153], v[36:39]
	v_mfma_f32_16x16x32_bf16 v[32:35], v[138:141], v[154:157], v[32:35]
	s_setprio 0
	ds_read_b128 v[138:141], v186 offset:1024
	s_waitcnt lgkmcnt(6)
	s_setprio 1
	v_mfma_f32_16x16x32_bf16 v[28:31], v[158:161], v[142:145], v[28:31]
	v_mfma_f32_16x16x32_bf16 v[24:27], v[158:161], v[146:149], v[24:27]
	s_setprio 0
	ds_read_b128 v[182:185], v186 offset:3072
	s_setprio 1
	v_mfma_f32_16x16x32_bf16 v[20:23], v[158:161], v[150:153], v[20:23]
	v_mfma_f32_16x16x32_bf16 v[16:19], v[158:161], v[154:157], v[16:19]
	s_setprio 0
	ds_read_b128 v[158:161], v186 offset:5120
	s_waitcnt lgkmcnt(7)
	s_setprio 1
	v_mfma_f32_16x16x32_bf16 v[12:15], v[162:165], v[142:145], v[12:15]
	v_mfma_f32_16x16x32_bf16 v[4:7], v[162:165], v[146:149], v[4:7]
	s_setprio 0
	ds_read_b128 v[142:145], v186 offset:7168
	s_setprio 1
	v_mfma_f32_16x16x32_bf16 v[0:3], v[162:165], v[150:153], v[0:3]
	v_mfma_f32_16x16x32_bf16 v[8:11], v[162:165], v[154:157], v[8:11]
	s_setprio 0
	ds_read_b128 v[188:191], v186 offset:9216
	s_waitcnt lgkmcnt(4)
	s_setprio 1
	v_mfma_f32_16x16x32_bf16 v[124:127], v[138:141], v[192:195], v[124:127]
	v_mfma_f32_16x16x32_bf16 v[120:123], v[138:141], v[196:199], v[120:123]
	v_mfma_f32_16x16x32_bf16 v[116:119], v[138:141], v[212:215], v[116:119]
	v_mfma_f32_16x16x32_bf16 v[112:115], v[138:141], v[216:219], v[112:115]
	s_setprio 0
	ds_read_b128 v[220:223], v186 offset:11264
	s_waitcnt lgkmcnt(4)
	s_setprio 1
	v_mfma_f32_16x16x32_bf16 v[108:111], v[182:185], v[192:195], v[108:111]
	v_mfma_f32_16x16x32_bf16 v[104:107], v[182:185], v[196:199], v[104:107]
	v_mfma_f32_16x16x32_bf16 v[100:103], v[182:185], v[212:215], v[100:103]
	v_mfma_f32_16x16x32_bf16 v[96:99], v[182:185], v[216:219], v[96:99]
	s_setprio 0
	ds_read_b128 v[224:227], v186 offset:13312
	s_waitcnt lgkmcnt(4)
	s_setprio 1
	v_mfma_f32_16x16x32_bf16 v[92:95], v[158:161], v[192:195], v[92:95]
	v_mfma_f32_16x16x32_bf16 v[88:91], v[158:161], v[196:199], v[88:91]
	v_mfma_f32_16x16x32_bf16 v[84:87], v[158:161], v[212:215], v[84:87]
	v_mfma_f32_16x16x32_bf16 v[80:83], v[158:161], v[216:219], v[80:83]
	s_setprio 0
	ds_read_b128 v[228:231], v186 offset:15360
	s_waitcnt lgkmcnt(4)
	s_setprio 1
	v_mfma_f32_16x16x32_bf16 v[76:79], v[142:145], v[192:195], v[76:79]
	v_mfma_f32_16x16x32_bf16 v[72:75], v[142:145], v[196:199], v[72:75]
	v_mfma_f32_16x16x32_bf16 v[68:71], v[142:145], v[212:215], v[68:71]
	v_mfma_f32_16x16x32_bf16 v[64:67], v[142:145], v[216:219], v[64:67]
	s_waitcnt lgkmcnt(0)
	s_setprio 0
	s_waitcnt vmcnt(0)
	s_add_i32 s13, s13, 64
	s_add_i32 s5, s5, 0x10000
	s_add_i32 s15, s15, 1
	s_cmpk_lg_i32 s13, 0x400
	s_waitcnt vmcnt(0)
	s_barrier
	s_cbranch_scc1 .LBB0_314
	v_mfma_f32_16x16x32_bf16 v[60:63], v[188:191], v[192:195], v[60:63]
	v_mfma_f32_16x16x32_bf16 v[56:59], v[188:191], v[196:199], v[56:59]
	v_mfma_f32_16x16x32_bf16 v[52:55], v[188:191], v[212:215], v[52:55]
	v_mfma_f32_16x16x32_bf16 v[48:51], v[188:191], v[216:219], v[48:51]
	v_mfma_f32_16x16x32_bf16 v[44:47], v[220:223], v[192:195], v[44:47]
	v_mfma_f32_16x16x32_bf16 v[40:43], v[220:223], v[196:199], v[40:43]
	v_mfma_f32_16x16x32_bf16 v[36:39], v[220:223], v[212:215], v[36:39]
	v_mfma_f32_16x16x32_bf16 v[32:35], v[220:223], v[216:219], v[32:35]
	v_mfma_f32_16x16x32_bf16 v[28:31], v[224:227], v[192:195], v[28:31]
	v_mfma_f32_16x16x32_bf16 v[24:27], v[224:227], v[196:199], v[24:27]
	v_mfma_f32_16x16x32_bf16 v[20:23], v[224:227], v[212:215], v[20:23]
	v_mfma_f32_16x16x32_bf16 v[16:19], v[224:227], v[216:219], v[16:19]
	v_mfma_f32_16x16x32_bf16 v[12:15], v[228:231], v[192:195], v[12:15]
	v_mfma_f32_16x16x32_bf16 v[4:7], v[228:231], v[196:199], v[4:7]
	v_mfma_f32_16x16x32_bf16 v[0:3], v[228:231], v[212:215], v[0:3]
	v_mfma_f32_16x16x32_bf16 v[8:11], v[228:231], v[216:219], v[8:11]
	s_nop 7
	s_nop 1

; DI float bflo(unsigned v) { return __uint_as_float(v << 16); }
; DI float bfhi(unsigned v) { return __uint_as_float(v & 0xffff0000u); }
; DI void phase_mla_up(const Params& P, int l, char* shm) {
;     ...
;       for (int i = 0; i < 8; ++i) {
;         const int chunk = tid_() + i * 512, row = chunk >> 4, j16 = chunk & 15, c8 = j16 * 8, t = brow + row;
;         const i32x4 v = *(const i32x4*)(shm + row * 272 + c8 * 2);
;         const u32x2 krr = *(const u32x2*)(projC + (size_t)t * 448 + 384 + j16 * 4);
;         float kv[8], kr[4];
; #pragma unroll
;         for (int e = 0; e < 4; ++e) { kv[2 * e] = bflo((unsigned)v[e]); kv[2 * e + 1] = bfhi((unsigned)v[e]); }
;         kr[0] = bflo(krr[0]); kr[1] = bfhi(krr[0]); kr[2] = bflo(krr[1]); kr[3] = bfhi(krr[1]);
;         float ss = 0.f;
; #pragma unroll
;         for (int e = 0; e < 8; ++e) ss += kv[e] * kv[e];
; #pragma unroll
;         for (int e = 0; e < 4; ++e) ss += kr[e] * kr[e];
;         ss += __shfl_xor(ss, 1); ss += __shfl_xor(ss, 2); ss += __shfl_xor(ss, 4); ss += __shfl_xor(ss, 8);
;         const float r = rsqrtf(ss * (1.f / 192.f) + EPS);
;         u16* kd = (u16*)(P.ws + OFF_KC) + ((size_t)((b * 4 + h) * SEQ + s0 + row)) * 192;
;         const f32x4 g0 = *(const f32x4*)(kng + c8), g1 = *(const f32x4*)(kng + c8 + 4);
;         i32x4 o;
;         o[0] = (int)pack2(kv[0] * r * g0[0], kv[1] * r * g0[1]);
;         o[1] = (int)pack2(kv[2] * r * g0[2], kv[3] * r * g0[3]);
;         o[2] = (int)pack2(kv[4] * r * g1[0], kv[5] * r * g1[1]);
;         o[3] = (int)pack2(kv[6] * r * g1[2], kv[7] * r * g1[3]);
;         *(i32x4*)(kd + c8) = o;
;         const f32x4 gr = *(const f32x4*)(kng + 128 + j16 * 4);
;         const f32x4* rt = (const f32x4*)(P.ws + OFF_ROPE) + (size_t)t * 16 + (j16 & 7) * 2;
;         const f32x4 cs01 = rt[0], cs23 = rt[1];
;         float my[4], ot[4], rv[4];
; #pragma unroll
;         for (int e = 0; e < 4; ++e) { my[e] = kr[e] * r * gr[e]; ot[e] = __shfl_xor(my[e], 8); }
;         const float sgn = (j16 < 8) ? -1.f : 1.f;
;         rv[0] = my[0] * cs01[0] + sgn * ot[0] * cs01[1];
;         rv[1] = my[1] * cs01[2] + sgn * ot[1] * cs01[3];
;         rv[2] = my[2] * cs23[0] + sgn * ot[2] * cs23[1];
;         rv[3] = my[3] * cs23[2] + sgn * ot[3] * cs23[3];
;         u32x2 ro = {pack2(rv[0], rv[1]), pack2(rv[2], rv[3])};
;         *(u32x2*)(kd + 128 + j16 * 4) = ro;
.LBB0_541:
	v_mov_b32_e32 v5, v135
	v_mov_b64_e32 v[18:19], s[10:11]
	v_add_u32_e32 v6, s5, v5
	v_ashrrev_i32_e32 v6, 4, v6
	v_and_b32_e32 v42, 15, v5
	v_add_u32_e32 v24, s25, v6
	v_lshlrev_b32_e32 v132, 3, v42
	v_mad_i64_i32 v[26:27], s[18:19], v24, s69, v[18:19]
	v_lshlrev_b32_e32 v5, 5, v5
	v_lshlrev_b32_e32 v22, 4, v42
	v_lshlrev_b32_e32 v10, 5, v42
	v_lshl_add_u64 v[26:27], v[26:27], 0, v[132:133]
	v_and_b32_e32 v20, 0xe0, v5
	v_mad_u64_u32 v[14:15], s[18:19], v6, s71, v[22:23]
	v_add_u32_e32 v5, s4, v6
	global_load_dwordx4 v[6:9], v10, s[12:13] offset:16
	s_nop 0
	global_load_dwordx4 v[10:13], v10, s[12:13]
	ds_read_b128 v[14:17], v14
	global_load_dwordx2 v[26:27], v[26:27], off offset:768
	v_ashrrev_i32_e32 v25, 31, v24
	v_lshlrev_b64 v[24:25], 8, v[24:25]
	v_mov_b32_e32 v21, v133
	v_lshl_add_u64 v[24:25], s[16:17], 0, v[24:25]
	s_waitcnt lgkmcnt(0)
	v_lshlrev_b32_e32 v34, 16, v14
	v_and_b32_e32 v35, 0xffff0000, v14
	v_mov_b64_e32 v[0:1], s[14:15]
	v_lshl_add_u64 v[20:21], v[24:25], 0, v[20:21]
	global_load_dwordx4 v[44:47], v22, s[12:13] offset:512
	global_load_dwordx4 v[96:99], v[20:21], off
	global_load_dwordx4 v[100:103], v[20:21], off offset:16
	v_mov_b64_e32 v[68:69], s[10:11]
	v_mov_b64_e32 v[50:51], s[14:15]
	v_mov_b32_e32 v55, v135
	v_mov_b32_e32 v75, v133
	v_mov_b32_e32 v73, v133
	v_add_u32_e32 v56, s5, v55
	v_add_u32_e32 v56, 0x200, v56
	v_ashrrev_i32_e32 v66, 4, v56
	v_and_b32_e32 v88, 15, v55
	v_add_u32_e32 v70, s25, v66
	v_lshlrev_b32_e32 v132, 3, v88
	v_mad_i64_i32 v[56:57], s[18:19], v70, s69, v[68:69]
	v_lshl_add_u64 v[56:57], v[56:57], 0, v[132:133]
	global_load_dwordx2 v[68:69], v[56:57], off offset:768
	v_lshlrev_b32_e32 v60, 5, v88
	global_load_dwordx4 v[56:59], v60, s[12:13] offset:16
	s_nop 0
	global_load_dwordx4 v[60:63], v60, s[12:13]
	v_lshlrev_b32_e32 v74, 4, v88
	v_lshlrev_b32_e32 v55, 5, v55
	v_mad_u64_u32 v[64:65], s[18:19], v66, s71, v[74:75]
	v_and_b32_e32 v72, 0xe0, v55
	v_add_u32_e32 v55, s4, v66
	ds_read_b128 v[64:67], v64
	v_ashrrev_i32_e32 v71, 31, v70
	v_lshlrev_b64 v[70:71], 8, v[70:71]
	v_lshl_add_u64 v[70:71], s[16:17], 0, v[70:71]
	v_lshl_add_u64 v[70:71], v[70:71], 0, v[72:73]
	global_load_dwordx4 v[164:167], v74, s[12:13] offset:512
	global_load_dwordx4 v[168:171], v[70:71], off
	global_load_dwordx4 v[172:175], v[70:71], off offset:16
	v_lshlrev_b32_e32 v24, 16, v17
	v_and_b32_e32 v25, 0xffff0000, v17
	v_lshlrev_b32_e32 v32, 16, v16
	v_and_b32_e32 v33, 0xffff0000, v16
	v_lshlrev_b32_e32 v16, 16, v15
	v_and_b32_e32 v17, 0xffff0000, v15
	v_pk_mul_f32 v[40:41], v[34:35], v[34:35]
	v_mad_i64_i32 v[28:29], s[18:19], v5, s83, v[0:1]
	v_pk_mul_f32 v[38:39], v[16:17], v[16:17]
	v_add_f32_e32 v5, v40, v41
	v_add_f32_e32 v5, v38, v5
	v_pk_mul_f32 v[36:37], v[32:33], v[32:33]
	v_add_f32_e32 v5, v39, v5
	v_add_f32_e32 v5, v36, v5
	v_pk_mul_f32 v[14:15], v[24:25], v[24:25]
	v_add_f32_e32 v5, v37, v5
	v_add_f32_e32 v5, v14, v5
	v_add_f32_e32 v5, v15, v5
	v_mov_b32_e32 v23, v133
	v_lshl_add_u64 v[30:31], v[28:29], 0, v[22:23]
	s_waitcnt vmcnt(0)
	v_lshlrev_b32_e32 v38, 16, v26
	v_and_b32_e32 v39, 0xffff0000, v26
	v_and_b32_e32 v36, 0xffff0000, v27
	v_lshlrev_b32_e32 v37, 16, v27
	v_pk_mul_f32 v[26:27], v[38:39], v[38:39]
	v_pk_mul_f32 v[14:15], v[36:37], v[36:37]
	v_add_f32_e32 v5, v26, v5
	v_add_f32_e32 v5, v27, v5
	v_add_f32_e32 v5, v15, v5
	v_add_f32_e32 v5, v14, v5
	ds_bpermute_b32 v14, v162, v5
	s_waitcnt lgkmcnt(0)
	v_add_f32_e32 v5, v5, v14
	ds_bpermute_b32 v14, v2, v5
	s_waitcnt lgkmcnt(0)
	v_add_f32_e32 v5, v5, v14
	ds_bpermute_b32 v14, v3, v5
	s_waitcnt lgkmcnt(0)
	v_add_f32_e32 v5, v5, v14
	ds_bpermute_b32 v14, v4, v5
	s_waitcnt lgkmcnt(0)
	v_add_f32_e32 v5, v5, v14
	v_fmamk_f32 v5, v5, 0x3baaaaab, v134
	v_mul_f32_e32 v14, 0x4b800000, v5
	v_cmp_gt_f32_e32 vcc, s33, v5
	s_nop 1
	v_cndmask_b32_e32 v5, v5, v14, vcc
	v_rsq_f32_e32 v5, v5
	s_nop 0
	v_mul_f32_e32 v14, 0x45800000, v5
	v_cndmask_b32_e32 v26, v5, v14, vcc
	v_pk_mul_f32 v[14:15], v[26:27], v[34:35] op_sel_hi:[0,1]
	v_pk_mul_f32 v[16:17], v[26:27], v[16:17] op_sel_hi:[0,1]
	v_pk_mul_f32 v[32:33], v[26:27], v[32:33] op_sel_hi:[0,1]
	v_pk_mul_f32 v[24:25], v[26:27], v[24:25] op_sel_hi:[0,1]
	v_pk_mul_f32 v[10:11], v[10:11], v[14:15]
	v_pk_mul_f32 v[12:13], v[12:13], v[16:17]
	v_pk_mul_f32 v[14:15], v[6:7], v[32:33]
	v_pk_mul_f32 v[16:17], v[8:9], v[24:25]
	v_cvt_pk_bf16_f32 v6, v10, v11
	v_cvt_pk_bf16_f32 v7, v12, v13
	v_cvt_pk_bf16_f32 v8, v14, v15
	v_cvt_pk_bf16_f32 v9, v16, v17
	global_store_dwordx4 v[30:31], v[6:9], off
	v_pk_mul_f32 v[24:25], v[26:27], v[38:39] op_sel_hi:[0,1]
	v_pk_mul_f32 v[26:27], v[26:27], v[36:37] op_sel_hi:[0,1]
	v_cmp_gt_u32_e32 vcc, 8, v42
	v_mov_b32_e32 v5, v135
	v_lshl_add_u64 v[22:23], v[28:29], 0, v[132:133]
	v_cndmask_b32_e64 v20, 1.0, -1.0, vcc
	v_pk_mul_f32 v[6:7], v[44:45], v[24:25]
	v_pk_mul_f32 v[8:9], v[46:47], v[26:27] op_sel:[0,1] op_sel_hi:[1,0]
	s_waitcnt lgkmcnt(0)
; DI void phase_mla_up(const Params& P, int l, char* shm) {
;     ...
;       for (int i = 0; i < 8; ++i) {
;         const int chunk = tid_() + i * 512, row = chunk >> 4, j16 = chunk & 15, c8 = j16 * 8, t = brow + row;
;         const i32x4 v = *(const i32x4*)(shm + row * 272 + c8 * 2);
;         const u32x2 krr = *(const u32x2*)(projC + (size_t)t * 448 + 384 + j16 * 4);
;         float kv[8], kr[4];
; #pragma unroll
;         for (int e = 0; e < 4; ++e) { kv[2 * e] = bflo((unsigned)v[e]); kv[2 * e + 1] = bfhi((unsigned)v[e]); }
;         kr[0] = bflo(krr[0]); kr[1] = bfhi(krr[0]); kr[2] = bflo(krr[1]); kr[3] = bfhi(krr[1]);
;         float ss = 0.f;
; #pragma unroll
;         for (int e = 0; e < 8; ++e) ss += kv[e] * kv[e];
; #pragma unroll
;         for (int e = 0; e < 4; ++e) ss += kr[e] * kr[e];
;         ss += __shfl_xor(ss, 1); ss += __shfl_xor(ss, 2); ss += __shfl_xor(ss, 4); ss += __shfl_xor(ss, 8);
;         const float r = rsqrtf(ss * (1.f / 192.f) + EPS);
;         u16* kd = (u16*)(P.ws + OFF_KC) + ((size_t)((b * 4 + h) * SEQ + s0 + row)) * 192;
;         const f32x4 g0 = *(const f32x4*)(kng + c8), g1 = *(const f32x4*)(kng + c8 + 4);
;         i32x4 o;
;         o[0] = (int)pack2(kv[0] * r * g0[0], kv[1] * r * g0[1]);
;         o[1] = (int)pack2(kv[2] * r * g0[2], kv[3] * r * g0[3]);
;         o[2] = (int)pack2(kv[4] * r * g1[0], kv[5] * r * g1[1]);
;         o[3] = (int)pack2(kv[6] * r * g1[2], kv[7] * r * g1[3]);
;         *(i32x4*)(kd + c8) = o;
;         const f32x4 gr = *(const f32x4*)(kng + 128 + j16 * 4);
;         const f32x4* rt = (const f32x4*)(P.ws + OFF_ROPE) + (size_t)t * 16 + (j16 & 7) * 2;
;         const f32x4 cs01 = rt[0], cs23 = rt[1];
;         float my[4], ot[4], rv[4];
; #pragma unroll
;         for (int e = 0; e < 4; ++e) { my[e] = kr[e] * r * gr[e]; ot[e] = __shfl_xor(my[e], 8); }
;         const float sgn = (j16 < 8) ? -1.f : 1.f;
;         rv[0] = my[0] * cs01[0] + sgn * ot[0] * cs01[1];
;         rv[1] = my[1] * cs01[2] + sgn * ot[1] * cs01[3];
;         rv[2] = my[2] * cs23[0] + sgn * ot[2] * cs23[1];
;         rv[3] = my[3] * cs23[2] + sgn * ot[3] * cs23[3];
;         u32x2 ro = {pack2(rv[0], rv[1]), pack2(rv[2], rv[3])};
;         *(u32x2*)(kd + 128 + j16 * 4) = ro;
;       }
; #pragma unroll 4
;       for (int i = 0; i < 8; ++i) {
;         const int chunk = tid_() + i * 512, dv = chunk >> 5, c8 = (chunk & 31) * 8;
	v_mov_b32_e32 v24, v96
	v_mov_b32_e32 v25, v98
	v_mov_b32_e32 v12, v97
	v_mov_b32_e32 v13, v99
	v_mov_b32_e32 v10, v100
	v_mov_b32_e32 v11, v102
	v_mov_b32_e32 v16, v101
	v_mov_b32_e32 v17, v103
	ds_bpermute_b32 v14, v4, v6
	ds_bpermute_b32 v15, v4, v7
	ds_bpermute_b32 v26, v4, v8
	ds_bpermute_b32 v27, v4, v9
	v_pk_mul_f32 v[6:7], v[24:25], v[6:7]
	v_pk_mul_f32 v[8:9], v[10:11], v[8:9]
	s_waitcnt lgkmcnt(2)
	v_pk_mul_f32 v[10:11], v[20:21], v[14:15] op_sel_hi:[0,1]
	v_pk_fma_f32 v[6:7], v[12:13], v[10:11], v[6:7]
	s_waitcnt lgkmcnt(0)
	v_pk_mul_f32 v[14:15], v[20:21], v[26:27] op_sel_hi:[0,1]
	v_pk_fma_f32 v[8:9], v[16:17], v[14:15], v[8:9]
	v_cvt_pk_bf16_f32 v6, v6, v7
	v_cvt_pk_bf16_f32 v7, v8, v9
	global_store_dwordx2 v[22:23], v[6:7], off offset:256
	s_waitcnt lgkmcnt(0)
	v_lshlrev_b32_e32 v80, 16, v64
	v_and_b32_e32 v81, 0xffff0000, v64
	v_lshlrev_b32_e32 v72, 16, v67
	v_and_b32_e32 v73, 0xffff0000, v67
	v_lshlrev_b32_e32 v78, 16, v66
	v_and_b32_e32 v79, 0xffff0000, v66
	v_lshlrev_b32_e32 v66, 16, v65
	v_and_b32_e32 v67, 0xffff0000, v65
	v_pk_mul_f32 v[86:87], v[80:81], v[80:81]
	v_mad_i64_i32 v[50:51], s[18:19], v55, s83, v[50:51]
	v_pk_mul_f32 v[84:85], v[66:67], v[66:67]
	v_add_f32_e32 v55, v86, v87
	v_add_f32_e32 v55, v84, v55
	v_pk_mul_f32 v[82:83], v[78:79], v[78:79]
	v_add_f32_e32 v55, v85, v55
	v_add_f32_e32 v55, v82, v55
	v_pk_mul_f32 v[64:65], v[72:73], v[72:73]
	v_add_f32_e32 v55, v83, v55
	v_add_f32_e32 v55, v64, v55
	v_add_f32_e32 v55, v65, v55
	v_mov_b32_e32 v75, v133
	v_lshl_add_u64 v[76:77], v[50:51], 0, v[74:75]
	s_addk_i32 s5, 0x400
	s_cmpk_eq_i32 s5, 0x1000
	v_lshl_add_u64 v[50:51], v[50:51], 0, v[132:133]
	v_lshlrev_b32_e32 v84, 16, v68
	v_and_b32_e32 v85, 0xffff0000, v68
	v_and_b32_e32 v82, 0xffff0000, v69
	v_lshlrev_b32_e32 v83, 16, v69
	v_pk_mul_f32 v[68:69], v[84:85], v[84:85]
	v_pk_mul_f32 v[64:65], v[82:83], v[82:83]
	v_add_f32_e32 v55, v68, v55
	v_add_f32_e32 v55, v69, v55
	v_add_f32_e32 v55, v65, v55
	v_add_f32_e32 v55, v64, v55
	ds_bpermute_b32 v64, v162, v55
	s_waitcnt lgkmcnt(0)
	v_add_f32_e32 v55, v55, v64
	ds_bpermute_b32 v64, v2, v55
	s_waitcnt lgkmcnt(0)
	v_add_f32_e32 v55, v55, v64
	ds_bpermute_b32 v64, v3, v55
	s_waitcnt lgkmcnt(0)
	v_add_f32_e32 v55, v55, v64
	ds_bpermute_b32 v64, v4, v55
	s_waitcnt lgkmcnt(0)
	v_add_f32_e32 v55, v55, v64
	v_fmamk_f32 v55, v55, 0x3baaaaab, v134
	v_mul_f32_e32 v64, 0x4b800000, v55
	v_cmp_gt_f32_e32 vcc, s33, v55
	s_nop 1
	v_cndmask_b32_e32 v55, v55, v64, vcc
	v_rsq_f32_e32 v55, v55
	s_nop 0
	v_mul_f32_e32 v64, 0x45800000, v55
	v_cndmask_b32_e32 v68, v55, v64, vcc
	v_pk_mul_f32 v[64:65], v[68:69], v[80:81] op_sel_hi:[0,1]
	v_pk_mul_f32 v[66:67], v[68:69], v[66:67] op_sel_hi:[0,1]
	v_pk_mul_f32 v[78:79], v[68:69], v[78:79] op_sel_hi:[0,1]
	v_pk_mul_f32 v[72:73], v[68:69], v[72:73] op_sel_hi:[0,1]
	v_pk_mul_f32 v[60:61], v[60:61], v[64:65]
	v_pk_mul_f32 v[62:63], v[62:63], v[66:67]
	v_pk_mul_f32 v[64:65], v[56:57], v[78:79]
	v_pk_mul_f32 v[66:67], v[58:59], v[72:73]
	v_cvt_pk_bf16_f32 v56, v60, v61
	v_cvt_pk_bf16_f32 v57, v62, v63
	v_cvt_pk_bf16_f32 v58, v64, v65
	v_cvt_pk_bf16_f32 v59, v66, v67
	global_store_dwordx4 v[76:77], v[56:59], off
	v_pk_mul_f32 v[72:73], v[68:69], v[84:85] op_sel_hi:[0,1]
	v_pk_mul_f32 v[68:69], v[68:69], v[82:83] op_sel_hi:[0,1]
	v_cmp_gt_u32_e32 vcc, 8, v88
	v_pk_mul_f32 v[56:57], v[164:165], v[72:73]
	v_pk_mul_f32 v[58:59], v[166:167], v[68:69] op_sel:[0,1] op_sel_hi:[1,0]
	s_waitcnt lgkmcnt(0)
	v_mov_b32_e32 v72, v168
	v_mov_b32_e32 v73, v170
	v_mov_b32_e32 v62, v169
	v_mov_b32_e32 v63, v171
	v_mov_b32_e32 v60, v172
	v_mov_b32_e32 v61, v174
	v_mov_b32_e32 v66, v173
	v_mov_b32_e32 v67, v175
	ds_bpermute_b32 v64, v4, v56
	ds_bpermute_b32 v65, v4, v57
	ds_bpermute_b32 v68, v4, v58
	ds_bpermute_b32 v69, v4, v59
	v_cndmask_b32_e64 v70, 1.0, -1.0, vcc
	v_pk_mul_f32 v[56:57], v[72:73], v[56:57]
	v_pk_mul_f32 v[58:59], v[60:61], v[58:59]
	s_waitcnt lgkmcnt(2)
	v_pk_mul_f32 v[60:61], v[70:71], v[64:65] op_sel_hi:[0,1]
	s_waitcnt lgkmcnt(0)
	v_pk_mul_f32 v[64:65], v[70:71], v[68:69] op_sel_hi:[0,1]
	v_pk_fma_f32 v[56:57], v[62:63], v[60:61], v[56:57]
	v_pk_fma_f32 v[58:59], v[66:67], v[64:65], v[58:59]
	v_cvt_pk_bf16_f32 v56, v56, v57
	v_cvt_pk_bf16_f32 v57, v58, v59
	global_store_dwordx2 v[50:51], v[56:57], off offset:256
	s_cbranch_scc0 .LBB0_541
	s_lshl_b32 s4, s1, 9
	s_lshl_b32 s1, s27, 7
	s_add_i32 s4, s4, s1
	s_lshl_b32 s0, s0, 1
	s_add_u32 s0, s22, s0
	s_addc_u32 s1, s23, 0
	s_mov_b32 s5, 0

; #define LDB_(dst, ks) _Pragma("unroll") for (int n = 0; n < 4; ++n) dst[n] = *(const bf16x8*)(sB + b_off + n * 2048 + (ks) * 1024)
; #define LDA_(dst, ks, h) _Pragma("unroll") for (int m = 0; m < 4; ++m) dst[m] = *(const bf16x8*)(sA + a_off + ((h) * 4 + m) * 2048 + (ks) * 1024)
; #define MMA_(A, B, h) _Pragma("unroll") for (int m = 0; m < 4; ++m) _Pragma("unroll") for (int n = 0; n < 4; ++n) \
;       acc[(h) * 4 + m][n] = SWAP ? MFMA16(B[n], A[m], acc[(h) * 4 + m][n]) : MFMA16(A[m], B[n], acc[(h) * 4 + m][n])
; template <int MF, int NF, bool SWAP = true>
; DI void gemm_main(f32x4 (&acc)[MF][NF], const u16* __restrict__ Ab, int lda, const u16* __restrict__ Bb, int ldb,
;                   int K, char* shm) {
;     ...
;     if constexpr (MF == 8 && NF == 4) {
;       bf16x8 B0[4], B1[4], A0[4], A1[4], A2[4], A3[4];
;     ...
;       LDB_(B0, 0); LDA_(A0, 0, 0);
;       LDA_(A1, 0, 1); MMA_(A0, B0, 0);
;       LDB_(B1, 1); LDA_(A2, 1, 0); MMA_(A1, B0, 1);
;       LDA_(A3, 1, 1); MMA_(A2, B1, 0);
;       MMA_(A3, B1, 1);
;     ...
;       __builtin_amdgcn_sched_group_barrier(0x100, 8, 0);
; #pragma unroll
;       for (int i = 0; i < 4; ++i) { __builtin_amdgcn_sched_group_barrier(0x100, 1, 0); __builtin_amdgcn_sched_group_barrier(0x008, 4, 0); }
; #pragma unroll
;       for (int i = 0; i < 8; ++i) { __builtin_amdgcn_sched_group_barrier(0x100, 1, 0); __builtin_amdgcn_sched_group_barrier(0x008, 2, 0); }
; #pragma unroll
;       for (int i = 0; i < 4; ++i) { __builtin_amdgcn_sched_group_barrier(0x100, 1, 0); __builtin_amdgcn_sched_group_barrier(0x008, 4, 0); }
;       __builtin_amdgcn_sched_group_barrier(0x008, 16, 0);
;       __builtin_amdgcn_sched_barrier(0);
;     ...
;     if constexpr (RING3) {
;       if (t + 2 < nt) asm volatile("s_waitcnt vmcnt(6)" ::: "memory");
;       else asm volatile("s_waitcnt vmcnt(0)" ::: "memory");
;       asm volatile("s_waitcnt lgkmcnt(0)" ::: "memory");
;       __builtin_amdgcn_s_barrier();
;       cur3 = (cur3 == 2) ? 0 : cur3 + 1;
;       nxt3 = (nxt3 == 2) ? 0 : nxt3 + 1;
;     } else {
;       asm volatile("s_waitcnt vmcnt(0)" ::: "memory");
;       __syncthreads();
;     }
.Lg_rot553_main:
	s_waitcnt lgkmcnt(4)
	s_setprio 1
	v_mfma_f32_16x16x32_bf16 v[124:127], v[146:149], v[162:165], v[124:127]
	v_mfma_f32_16x16x32_bf16 v[120:123], v[150:153], v[162:165], v[120:123]
	v_mfma_f32_16x16x32_bf16 v[116:119], v[154:157], v[162:165], v[116:119]
	v_mfma_f32_16x16x32_bf16 v[112:115], v[158:161], v[162:165], v[112:115]
	s_setprio 0
	ds_read_b128 v[162:165], v194 offset:10240
	s_waitcnt lgkmcnt(4)
	s_setprio 1
	v_mfma_f32_16x16x32_bf16 v[108:111], v[146:149], v[166:169], v[108:111]
	v_mfma_f32_16x16x32_bf16 v[104:107], v[150:153], v[166:169], v[104:107]
	v_mfma_f32_16x16x32_bf16 v[100:103], v[154:157], v[166:169], v[100:103]
	v_mfma_f32_16x16x32_bf16 v[96:99], v[158:161], v[166:169], v[96:99]
	s_setprio 0
	ds_read_b128 v[166:169], v194 offset:12288
	s_waitcnt lgkmcnt(4)
	s_setprio 1
	v_mfma_f32_16x16x32_bf16 v[92:95], v[146:149], v[170:173], v[92:95]
	v_mfma_f32_16x16x32_bf16 v[88:91], v[150:153], v[170:173], v[88:91]
	v_mfma_f32_16x16x32_bf16 v[84:87], v[154:157], v[170:173], v[84:87]
	v_mfma_f32_16x16x32_bf16 v[80:83], v[158:161], v[170:173], v[80:83]
	s_setprio 0
	ds_read_b128 v[170:173], v194 offset:14336
	s_waitcnt lgkmcnt(4)
	s_setprio 1
	v_mfma_f32_16x16x32_bf16 v[76:79], v[146:149], v[174:177], v[76:79]
	v_mfma_f32_16x16x32_bf16 v[72:75], v[150:153], v[174:177], v[72:75]
	v_mfma_f32_16x16x32_bf16 v[68:71], v[154:157], v[174:177], v[68:71]
	v_mfma_f32_16x16x32_bf16 v[64:67], v[158:161], v[174:177], v[64:67]
	s_setprio 0
	ds_read_b128 v[196:199], v186 offset:33792
	s_waitcnt lgkmcnt(4)
	s_setprio 1
	v_mfma_f32_16x16x32_bf16 v[60:63], v[146:149], v[178:181], v[60:63]
	v_mfma_f32_16x16x32_bf16 v[56:59], v[150:153], v[178:181], v[56:59]
	s_setprio 0
	ds_read_b128 v[216:219], v186 offset:35840
	s_setprio 1
	v_mfma_f32_16x16x32_bf16 v[52:55], v[154:157], v[178:181], v[52:55]
	v_mfma_f32_16x16x32_bf16 v[48:51], v[158:161], v[178:181], v[48:51]
	s_setprio 0
	ds_read_b128 v[220:223], v186 offset:37888
	s_waitcnt lgkmcnt(5)
	s_setprio 1
	v_mfma_f32_16x16x32_bf16 v[44:47], v[146:149], v[162:165], v[44:47]
	v_mfma_f32_16x16x32_bf16 v[40:43], v[150:153], v[162:165], v[40:43]
	s_setprio 0
	ds_read_b128 v[224:227], v186 offset:39936
	s_setprio 1
	v_mfma_f32_16x16x32_bf16 v[36:39], v[154:157], v[162:165], v[36:39]
	v_mfma_f32_16x16x32_bf16 v[32:35], v[158:161], v[162:165], v[32:35]
	s_setprio 0
	ds_read_b128 v[162:165], v194 offset:1024
	s_waitcnt lgkmcnt(6)
	s_setprio 1
	v_mfma_f32_16x16x32_bf16 v[28:31], v[146:149], v[166:169], v[28:31]
	v_mfma_f32_16x16x32_bf16 v[24:27], v[150:153], v[166:169], v[24:27]
	s_setprio 0
	ds_read_b128 v[190:193], v194 offset:3072
	s_setprio 1
	v_mfma_f32_16x16x32_bf16 v[20:23], v[154:157], v[166:169], v[20:23]
	v_mfma_f32_16x16x32_bf16 v[16:19], v[158:161], v[166:169], v[16:19]
	s_setprio 0
	ds_read_b128 v[166:169], v194 offset:5120
	s_waitcnt lgkmcnt(7)
	s_setprio 1
	v_mfma_f32_16x16x32_bf16 v[12:15], v[146:149], v[170:173], v[12:15]
	v_mfma_f32_16x16x32_bf16 v[4:7], v[150:153], v[170:173], v[4:7]
	s_setprio 0
	ds_read_b128 v[146:149], v194 offset:7168
	s_setprio 1
	v_mfma_f32_16x16x32_bf16 v[0:3], v[154:157], v[170:173], v[0:3]
	v_mfma_f32_16x16x32_bf16 v[8:11], v[158:161], v[170:173], v[8:11]
	s_setprio 0
	ds_read_b128 v[212:215], v194 offset:9216
	s_waitcnt lgkmcnt(4)
	s_setprio 1
	v_mfma_f32_16x16x32_bf16 v[124:127], v[196:199], v[162:165], v[124:127]
	v_mfma_f32_16x16x32_bf16 v[120:123], v[216:219], v[162:165], v[120:123]
	v_mfma_f32_16x16x32_bf16 v[116:119], v[220:223], v[162:165], v[116:119]
	v_mfma_f32_16x16x32_bf16 v[112:115], v[224:227], v[162:165], v[112:115]
	s_setprio 0
	ds_read_b128 v[228:231], v194 offset:11264
	s_waitcnt lgkmcnt(4)
	s_setprio 1
	v_mfma_f32_16x16x32_bf16 v[108:111], v[196:199], v[190:193], v[108:111]
	v_mfma_f32_16x16x32_bf16 v[104:107], v[216:219], v[190:193], v[104:107]
	v_mfma_f32_16x16x32_bf16 v[100:103], v[220:223], v[190:193], v[100:103]
	v_mfma_f32_16x16x32_bf16 v[96:99], v[224:227], v[190:193], v[96:99]
	s_setprio 0
	ds_read_b128 v[232:235], v194 offset:13312
	s_waitcnt lgkmcnt(4)
	s_setprio 1
	v_mfma_f32_16x16x32_bf16 v[92:95], v[196:199], v[166:169], v[92:95]
	v_mfma_f32_16x16x32_bf16 v[88:91], v[216:219], v[166:169], v[88:91]
	v_mfma_f32_16x16x32_bf16 v[84:87], v[220:223], v[166:169], v[84:87]
	v_mfma_f32_16x16x32_bf16 v[80:83], v[224:227], v[166:169], v[80:83]
	s_setprio 0
	ds_read_b128 v[236:239], v194 offset:15360
	s_waitcnt lgkmcnt(4)
	s_setprio 1
	v_mfma_f32_16x16x32_bf16 v[76:79], v[196:199], v[146:149], v[76:79]
	v_mfma_f32_16x16x32_bf16 v[72:75], v[216:219], v[146:149], v[72:75]
	v_mfma_f32_16x16x32_bf16 v[68:71], v[220:223], v[146:149], v[68:71]
	v_mfma_f32_16x16x32_bf16 v[64:67], v[224:227], v[146:149], v[64:67]
	s_waitcnt lgkmcnt(0)
	s_setprio 0
	s_waitcnt vmcnt(0)
	s_add_i32 s19, s19, 64
	s_add_i32 s18, s18, 0x10000
	s_add_i32 s20, s20, 1
	s_cmpk_lg_i32 s19, 0x100
	s_waitcnt vmcnt(0)
	s_barrier
	s_cbranch_scc1 .LBB0_553
	v_mfma_f32_16x16x32_bf16 v[60:63], v[196:199], v[212:215], v[60:63]
	v_mfma_f32_16x16x32_bf16 v[56:59], v[216:219], v[212:215], v[56:59]
	v_mfma_f32_16x16x32_bf16 v[52:55], v[220:223], v[212:215], v[52:55]
	v_mfma_f32_16x16x32_bf16 v[48:51], v[224:227], v[212:215], v[48:51]
	v_mfma_f32_16x16x32_bf16 v[44:47], v[196:199], v[228:231], v[44:47]
	v_mfma_f32_16x16x32_bf16 v[40:43], v[216:219], v[228:231], v[40:43]
	v_mfma_f32_16x16x32_bf16 v[36:39], v[220:223], v[228:231], v[36:39]
	v_mfma_f32_16x16x32_bf16 v[32:35], v[224:227], v[228:231], v[32:35]
	v_mfma_f32_16x16x32_bf16 v[28:31], v[196:199], v[232:235], v[28:31]
	v_mfma_f32_16x16x32_bf16 v[24:27], v[216:219], v[232:235], v[24:27]
	v_mfma_f32_16x16x32_bf16 v[20:23], v[220:223], v[232:235], v[20:23]
	v_mfma_f32_16x16x32_bf16 v[16:19], v[224:227], v[232:235], v[16:19]
	v_mfma_f32_16x16x32_bf16 v[12:15], v[196:199], v[236:239], v[12:15]
	v_mfma_f32_16x16x32_bf16 v[4:7], v[216:219], v[236:239], v[4:7]
	v_mfma_f32_16x16x32_bf16 v[0:3], v[220:223], v[236:239], v[0:3]
	v_mfma_f32_16x16x32_bf16 v[8:11], v[224:227], v[236:239], v[8:11]
	s_nop 7
	s_nop 1

; #define LDB_(dst, ks) _Pragma("unroll") for (int n = 0; n < 4; ++n) dst[n] = *(const bf16x8*)(sB + b_off + n * 2048 + (ks) * 1024)
; #define LDA_(dst, ks, h) _Pragma("unroll") for (int m = 0; m < 4; ++m) dst[m] = *(const bf16x8*)(sA + a_off + ((h) * 4 + m) * 2048 + (ks) * 1024)
; #define MMA_(A, B, h) _Pragma("unroll") for (int m = 0; m < 4; ++m) _Pragma("unroll") for (int n = 0; n < 4; ++n) \
;       acc[(h) * 4 + m][n] = SWAP ? MFMA16(B[n], A[m], acc[(h) * 4 + m][n]) : MFMA16(A[m], B[n], acc[(h) * 4 + m][n])
; template <int MF, int NF, bool SWAP = true>
; DI void gemm_main(f32x4 (&acc)[MF][NF], const u16* __restrict__ Ab, int lda, const u16* __restrict__ Bb, int ldb,
;                   int K, char* shm) {
;     ...
;     if constexpr (MF == 8 && NF == 4) {
;       bf16x8 B0[4], B1[4], A0[4], A1[4], A2[4], A3[4];
;     ...
;       LDB_(B0, 0); LDA_(A0, 0, 0);
;       LDA_(A1, 0, 1); MMA_(A0, B0, 0);
;       LDB_(B1, 1); LDA_(A2, 1, 0); MMA_(A1, B0, 1);
;       LDA_(A3, 1, 1); MMA_(A2, B1, 0);
;       MMA_(A3, B1, 1);
;     ...
;       __builtin_amdgcn_sched_group_barrier(0x100, 8, 0);
; #pragma unroll
;       for (int i = 0; i < 4; ++i) { __builtin_amdgcn_sched_group_barrier(0x100, 1, 0); __builtin_amdgcn_sched_group_barrier(0x008, 4, 0); }
; #pragma unroll
;       for (int i = 0; i < 8; ++i) { __builtin_amdgcn_sched_group_barrier(0x100, 1, 0); __builtin_amdgcn_sched_group_barrier(0x008, 2, 0); }
; #pragma unroll
;       for (int i = 0; i < 4; ++i) { __builtin_amdgcn_sched_group_barrier(0x100, 1, 0); __builtin_amdgcn_sched_group_barrier(0x008, 4, 0); }
;       __builtin_amdgcn_sched_group_barrier(0x008, 16, 0);
;       __builtin_amdgcn_sched_barrier(0);
;     ...
;     if constexpr (RING3) {
;       if (t + 2 < nt) asm volatile("s_waitcnt vmcnt(6)" ::: "memory");
;       else asm volatile("s_waitcnt vmcnt(0)" ::: "memory");
;       asm volatile("s_waitcnt lgkmcnt(0)" ::: "memory");
;       __builtin_amdgcn_s_barrier();
;       cur3 = (cur3 == 2) ? 0 : cur3 + 1;
;       nxt3 = (nxt3 == 2) ? 0 : nxt3 + 1;
;     } else {
;       asm volatile("s_waitcnt vmcnt(0)" ::: "memory");
;       __syncthreads();
;     }
.Lg_rot589_main:
	s_waitcnt lgkmcnt(4)
	s_setprio 1
	v_mfma_f32_16x16x32_bf16 v[124:127], v[138:141], v[154:157], v[124:127]
	v_mfma_f32_16x16x32_bf16 v[120:123], v[142:145], v[154:157], v[120:123]
	v_mfma_f32_16x16x32_bf16 v[116:119], v[146:149], v[154:157], v[116:119]
	v_mfma_f32_16x16x32_bf16 v[112:115], v[150:153], v[154:157], v[112:115]
	s_setprio 0
	ds_read_b128 v[154:157], v137 offset:10240
	s_waitcnt lgkmcnt(4)
	s_setprio 1
	v_mfma_f32_16x16x32_bf16 v[108:111], v[138:141], v[158:161], v[108:111]
	v_mfma_f32_16x16x32_bf16 v[104:107], v[142:145], v[158:161], v[104:107]
	v_mfma_f32_16x16x32_bf16 v[100:103], v[146:149], v[158:161], v[100:103]
	v_mfma_f32_16x16x32_bf16 v[96:99], v[150:153], v[158:161], v[96:99]
	s_setprio 0
	ds_read_b128 v[158:161], v137 offset:12288
	s_waitcnt lgkmcnt(4)
	s_setprio 1
	v_mfma_f32_16x16x32_bf16 v[92:95], v[138:141], v[162:165], v[92:95]
	v_mfma_f32_16x16x32_bf16 v[88:91], v[142:145], v[162:165], v[88:91]
	v_mfma_f32_16x16x32_bf16 v[84:87], v[146:149], v[162:165], v[84:87]
	v_mfma_f32_16x16x32_bf16 v[80:83], v[150:153], v[162:165], v[80:83]
	s_setprio 0
	ds_read_b128 v[162:165], v137 offset:14336
	s_waitcnt lgkmcnt(4)
	s_setprio 1
	v_mfma_f32_16x16x32_bf16 v[76:79], v[138:141], v[166:169], v[76:79]
	v_mfma_f32_16x16x32_bf16 v[72:75], v[142:145], v[166:169], v[72:75]
	v_mfma_f32_16x16x32_bf16 v[68:71], v[146:149], v[166:169], v[68:71]
	v_mfma_f32_16x16x32_bf16 v[64:67], v[150:153], v[166:169], v[64:67]
	s_setprio 0
	ds_read_b128 v[186:189], v178 offset:33792
	s_waitcnt lgkmcnt(4)
	s_setprio 1
	v_mfma_f32_16x16x32_bf16 v[60:63], v[138:141], v[170:173], v[60:63]
	v_mfma_f32_16x16x32_bf16 v[56:59], v[142:145], v[170:173], v[56:59]
	s_setprio 0
	ds_read_b128 v[194:197], v178 offset:35840
	s_setprio 1
	v_mfma_f32_16x16x32_bf16 v[52:55], v[146:149], v[170:173], v[52:55]
	v_mfma_f32_16x16x32_bf16 v[48:51], v[150:153], v[170:173], v[48:51]
	s_setprio 0
	ds_read_b128 v[198:201], v178 offset:37888
	s_waitcnt lgkmcnt(5)
	s_setprio 1
	v_mfma_f32_16x16x32_bf16 v[44:47], v[138:141], v[154:157], v[44:47]
	v_mfma_f32_16x16x32_bf16 v[40:43], v[142:145], v[154:157], v[40:43]
	s_setprio 0
	ds_read_b128 v[218:221], v178 offset:39936
	s_setprio 1
	v_mfma_f32_16x16x32_bf16 v[36:39], v[146:149], v[154:157], v[36:39]
	v_mfma_f32_16x16x32_bf16 v[32:35], v[150:153], v[154:157], v[32:35]
	s_setprio 0
	ds_read_b128 v[154:157], v137 offset:1024
	s_waitcnt lgkmcnt(6)
	s_setprio 1
	v_mfma_f32_16x16x32_bf16 v[28:31], v[138:141], v[158:161], v[28:31]
	v_mfma_f32_16x16x32_bf16 v[24:27], v[142:145], v[158:161], v[24:27]
	s_setprio 0
	ds_read_b128 v[182:185], v137 offset:3072
	s_setprio 1
	v_mfma_f32_16x16x32_bf16 v[20:23], v[146:149], v[158:161], v[20:23]
	v_mfma_f32_16x16x32_bf16 v[16:19], v[150:153], v[158:161], v[16:19]
	s_setprio 0
	ds_read_b128 v[158:161], v137 offset:5120
	s_waitcnt lgkmcnt(7)
	s_setprio 1
	v_mfma_f32_16x16x32_bf16 v[12:15], v[138:141], v[162:165], v[12:15]
	v_mfma_f32_16x16x32_bf16 v[8:11], v[142:145], v[162:165], v[8:11]
	s_setprio 0
	ds_read_b128 v[138:141], v137 offset:7168
	s_setprio 1
	v_mfma_f32_16x16x32_bf16 v[4:7], v[146:149], v[162:165], v[4:7]
	v_mfma_f32_16x16x32_bf16 v[0:3], v[150:153], v[162:165], v[0:3]
	s_setprio 0
	ds_read_b128 v[190:193], v137 offset:9216
	s_waitcnt lgkmcnt(4)
	s_setprio 1
	v_mfma_f32_16x16x32_bf16 v[124:127], v[186:189], v[154:157], v[124:127]
	v_mfma_f32_16x16x32_bf16 v[120:123], v[194:197], v[154:157], v[120:123]
	v_mfma_f32_16x16x32_bf16 v[116:119], v[198:201], v[154:157], v[116:119]
	v_mfma_f32_16x16x32_bf16 v[112:115], v[218:221], v[154:157], v[112:115]
	s_setprio 0
	ds_read_b128 v[222:225], v137 offset:11264
	s_waitcnt lgkmcnt(4)
	s_setprio 1
	v_mfma_f32_16x16x32_bf16 v[108:111], v[186:189], v[182:185], v[108:111]
	v_mfma_f32_16x16x32_bf16 v[104:107], v[194:197], v[182:185], v[104:107]
	v_mfma_f32_16x16x32_bf16 v[100:103], v[198:201], v[182:185], v[100:103]
	v_mfma_f32_16x16x32_bf16 v[96:99], v[218:221], v[182:185], v[96:99]
	s_setprio 0
	ds_read_b128 v[226:229], v137 offset:13312
	s_waitcnt lgkmcnt(4)
	s_setprio 1
	v_mfma_f32_16x16x32_bf16 v[92:95], v[186:189], v[158:161], v[92:95]
	v_mfma_f32_16x16x32_bf16 v[88:91], v[194:197], v[158:161], v[88:91]
	v_mfma_f32_16x16x32_bf16 v[84:87], v[198:201], v[158:161], v[84:87]
	v_mfma_f32_16x16x32_bf16 v[80:83], v[218:221], v[158:161], v[80:83]
	s_setprio 0
	ds_read_b128 v[230:233], v137 offset:15360
	s_waitcnt lgkmcnt(4)
	s_setprio 1
	v_mfma_f32_16x16x32_bf16 v[76:79], v[186:189], v[138:141], v[76:79]
	v_mfma_f32_16x16x32_bf16 v[72:75], v[194:197], v[138:141], v[72:75]
	v_mfma_f32_16x16x32_bf16 v[68:71], v[198:201], v[138:141], v[68:71]
	v_mfma_f32_16x16x32_bf16 v[64:67], v[218:221], v[138:141], v[64:67]
	s_waitcnt lgkmcnt(0)
	s_setprio 0
	s_waitcnt vmcnt(0)
	s_add_i32 s13, s13, 64
	s_add_i32 s16, s16, 0x10000
	s_add_i32 s15, s15, 1
	s_cmpk_lg_i32 s13, 0x400
	s_waitcnt vmcnt(0)
	s_barrier
	s_cbranch_scc1 .LBB0_589
	v_mfma_f32_16x16x32_bf16 v[60:63], v[186:189], v[190:193], v[60:63]
	v_mfma_f32_16x16x32_bf16 v[56:59], v[194:197], v[190:193], v[56:59]
	v_mfma_f32_16x16x32_bf16 v[52:55], v[198:201], v[190:193], v[52:55]
	v_mfma_f32_16x16x32_bf16 v[48:51], v[218:221], v[190:193], v[48:51]
	v_mfma_f32_16x16x32_bf16 v[44:47], v[186:189], v[222:225], v[44:47]
	v_mfma_f32_16x16x32_bf16 v[40:43], v[194:197], v[222:225], v[40:43]
	v_mfma_f32_16x16x32_bf16 v[36:39], v[198:201], v[222:225], v[36:39]
	v_mfma_f32_16x16x32_bf16 v[32:35], v[218:221], v[222:225], v[32:35]
	v_mfma_f32_16x16x32_bf16 v[28:31], v[186:189], v[226:229], v[28:31]
	v_mfma_f32_16x16x32_bf16 v[24:27], v[194:197], v[226:229], v[24:27]
	v_mfma_f32_16x16x32_bf16 v[20:23], v[198:201], v[226:229], v[20:23]
	v_mfma_f32_16x16x32_bf16 v[16:19], v[218:221], v[226:229], v[16:19]
	v_mfma_f32_16x16x32_bf16 v[12:15], v[186:189], v[230:233], v[12:15]
	v_mfma_f32_16x16x32_bf16 v[8:11], v[194:197], v[230:233], v[8:11]
	v_mfma_f32_16x16x32_bf16 v[4:7], v[198:201], v[230:233], v[4:7]
	v_mfma_f32_16x16x32_bf16 v[0:3], v[218:221], v[230:233], v[0:3]
	s_nop 7
	s_nop 1

; #define LDB_(dst, ks) _Pragma("unroll") for (int n = 0; n < 4; ++n) dst[n] = *(const bf16x8*)(sB + b_off + n * 2048 + (ks) * 1024)
; #define LDA_(dst, ks, h) _Pragma("unroll") for (int m = 0; m < 4; ++m) dst[m] = *(const bf16x8*)(sA + a_off + ((h) * 4 + m) * 2048 + (ks) * 1024)
; #define MMA_(A, B, h) _Pragma("unroll") for (int m = 0; m < 4; ++m) _Pragma("unroll") for (int n = 0; n < 4; ++n) \
;       acc[(h) * 4 + m][n] = SWAP ? MFMA16(B[n], A[m], acc[(h) * 4 + m][n]) : MFMA16(A[m], B[n], acc[(h) * 4 + m][n])
; template <int MF, int NF, bool SWAP = true>
; DI void gemm_main(f32x4 (&acc)[MF][NF], const u16* __restrict__ Ab, int lda, const u16* __restrict__ Bb, int ldb,
;                   int K, char* shm) {
;     ...
;     if constexpr (MF == 8 && NF == 4) {
;       bf16x8 B0[4], B1[4], A0[4], A1[4], A2[4], A3[4];
;     ...
;       LDB_(B0, 0); LDA_(A0, 0, 0);
;       LDA_(A1, 0, 1); MMA_(A0, B0, 0);
;       LDB_(B1, 1); LDA_(A2, 1, 0); MMA_(A1, B0, 1);
;       LDA_(A3, 1, 1); MMA_(A2, B1, 0);
;       MMA_(A3, B1, 1);
;     ...
;       __builtin_amdgcn_sched_group_barrier(0x100, 8, 0);
; #pragma unroll
;       for (int i = 0; i < 4; ++i) { __builtin_amdgcn_sched_group_barrier(0x100, 1, 0); __builtin_amdgcn_sched_group_barrier(0x008, 4, 0); }
; #pragma unroll
;       for (int i = 0; i < 8; ++i) { __builtin_amdgcn_sched_group_barrier(0x100, 1, 0); __builtin_amdgcn_sched_group_barrier(0x008, 2, 0); }
; #pragma unroll
;       for (int i = 0; i < 4; ++i) { __builtin_amdgcn_sched_group_barrier(0x100, 1, 0); __builtin_amdgcn_sched_group_barrier(0x008, 4, 0); }
;       __builtin_amdgcn_sched_group_barrier(0x008, 16, 0);
;       __builtin_amdgcn_sched_barrier(0);
;     ...
;     if constexpr (RING3) {
;       if (t + 2 < nt) asm volatile("s_waitcnt vmcnt(6)" ::: "memory");
;       else asm volatile("s_waitcnt vmcnt(0)" ::: "memory");
;       asm volatile("s_waitcnt lgkmcnt(0)" ::: "memory");
;       __builtin_amdgcn_s_barrier();
;       cur3 = (cur3 == 2) ? 0 : cur3 + 1;
;       nxt3 = (nxt3 == 2) ? 0 : nxt3 + 1;
;     } else {
;       asm volatile("s_waitcnt vmcnt(0)" ::: "memory");
;       __syncthreads();
;     }
.Lg_rot819_main:
	s_waitcnt lgkmcnt(4)
	s_setprio 1
	v_mfma_f32_16x16x32_bf16 v[124:127], v[138:141], v[154:157], v[124:127]
	v_mfma_f32_16x16x32_bf16 v[120:123], v[142:145], v[154:157], v[120:123]
	v_mfma_f32_16x16x32_bf16 v[116:119], v[146:149], v[154:157], v[116:119]
	v_mfma_f32_16x16x32_bf16 v[112:115], v[150:153], v[154:157], v[112:115]
	s_setprio 0
	ds_read_b128 v[154:157], v137 offset:10240
	s_waitcnt lgkmcnt(4)
	s_setprio 1
	v_mfma_f32_16x16x32_bf16 v[108:111], v[138:141], v[158:161], v[108:111]
	v_mfma_f32_16x16x32_bf16 v[104:107], v[142:145], v[158:161], v[104:107]
	v_mfma_f32_16x16x32_bf16 v[100:103], v[146:149], v[158:161], v[100:103]
	v_mfma_f32_16x16x32_bf16 v[96:99], v[150:153], v[158:161], v[96:99]
	s_setprio 0
	ds_read_b128 v[158:161], v137 offset:12288
	s_waitcnt lgkmcnt(4)
	s_setprio 1
	v_mfma_f32_16x16x32_bf16 v[92:95], v[138:141], v[162:165], v[92:95]
	v_mfma_f32_16x16x32_bf16 v[88:91], v[142:145], v[162:165], v[88:91]
	v_mfma_f32_16x16x32_bf16 v[84:87], v[146:149], v[162:165], v[84:87]
	v_mfma_f32_16x16x32_bf16 v[80:83], v[150:153], v[162:165], v[80:83]
	s_setprio 0
	ds_read_b128 v[162:165], v137 offset:14336
	s_waitcnt lgkmcnt(4)
	s_setprio 1
	v_mfma_f32_16x16x32_bf16 v[76:79], v[138:141], v[166:169], v[76:79]
	v_mfma_f32_16x16x32_bf16 v[72:75], v[142:145], v[166:169], v[72:75]
	v_mfma_f32_16x16x32_bf16 v[68:71], v[146:149], v[166:169], v[68:71]
	v_mfma_f32_16x16x32_bf16 v[64:67], v[150:153], v[166:169], v[64:67]
	s_setprio 0
	ds_read_b128 v[186:189], v178 offset:33792
	s_waitcnt lgkmcnt(4)
	s_setprio 1
	v_mfma_f32_16x16x32_bf16 v[60:63], v[138:141], v[170:173], v[60:63]
	v_mfma_f32_16x16x32_bf16 v[56:59], v[142:145], v[170:173], v[56:59]
	s_setprio 0
	ds_read_b128 v[194:197], v178 offset:35840
	s_setprio 1
	v_mfma_f32_16x16x32_bf16 v[52:55], v[146:149], v[170:173], v[52:55]
	v_mfma_f32_16x16x32_bf16 v[48:51], v[150:153], v[170:173], v[48:51]
	s_setprio 0
	ds_read_b128 v[198:201], v178 offset:37888
	s_waitcnt lgkmcnt(5)
	s_setprio 1
	v_mfma_f32_16x16x32_bf16 v[44:47], v[138:141], v[154:157], v[44:47]
	v_mfma_f32_16x16x32_bf16 v[40:43], v[142:145], v[154:157], v[40:43]
	s_setprio 0
	ds_read_b128 v[218:221], v178 offset:39936
	s_setprio 1
	v_mfma_f32_16x16x32_bf16 v[36:39], v[146:149], v[154:157], v[36:39]
	v_mfma_f32_16x16x32_bf16 v[32:35], v[150:153], v[154:157], v[32:35]
	s_setprio 0
	ds_read_b128 v[154:157], v137 offset:1024
	s_waitcnt lgkmcnt(6)
	s_setprio 1
	v_mfma_f32_16x16x32_bf16 v[28:31], v[138:141], v[158:161], v[28:31]
	v_mfma_f32_16x16x32_bf16 v[24:27], v[142:145], v[158:161], v[24:27]
	s_setprio 0
	ds_read_b128 v[182:185], v137 offset:3072
	s_setprio 1
	v_mfma_f32_16x16x32_bf16 v[20:23], v[146:149], v[158:161], v[20:23]
	v_mfma_f32_16x16x32_bf16 v[16:19], v[150:153], v[158:161], v[16:19]
	s_setprio 0
	ds_read_b128 v[158:161], v137 offset:5120
	s_waitcnt lgkmcnt(7)
	s_setprio 1
	v_mfma_f32_16x16x32_bf16 v[8:11], v[138:141], v[162:165], v[8:11]
	v_mfma_f32_16x16x32_bf16 v[4:7], v[142:145], v[162:165], v[4:7]
	s_setprio 0
	ds_read_b128 v[138:141], v137 offset:7168
	s_setprio 1
	v_mfma_f32_16x16x32_bf16 v[0:3], v[146:149], v[162:165], v[0:3]
	v_mfma_f32_16x16x32_bf16 v[12:15], v[150:153], v[162:165], v[12:15]
	s_setprio 0
	ds_read_b128 v[190:193], v137 offset:9216
	s_waitcnt lgkmcnt(4)
	s_setprio 1
	v_mfma_f32_16x16x32_bf16 v[124:127], v[186:189], v[154:157], v[124:127]
	v_mfma_f32_16x16x32_bf16 v[120:123], v[194:197], v[154:157], v[120:123]
	v_mfma_f32_16x16x32_bf16 v[116:119], v[198:201], v[154:157], v[116:119]
	v_mfma_f32_16x16x32_bf16 v[112:115], v[218:221], v[154:157], v[112:115]
	s_setprio 0
	ds_read_b128 v[222:225], v137 offset:11264
	s_waitcnt lgkmcnt(4)
	s_setprio 1
	v_mfma_f32_16x16x32_bf16 v[108:111], v[186:189], v[182:185], v[108:111]
	v_mfma_f32_16x16x32_bf16 v[104:107], v[194:197], v[182:185], v[104:107]
	v_mfma_f32_16x16x32_bf16 v[100:103], v[198:201], v[182:185], v[100:103]
	v_mfma_f32_16x16x32_bf16 v[96:99], v[218:221], v[182:185], v[96:99]
	s_setprio 0
	ds_read_b128 v[226:229], v137 offset:13312
	s_waitcnt lgkmcnt(4)
	s_setprio 1
	v_mfma_f32_16x16x32_bf16 v[92:95], v[186:189], v[158:161], v[92:95]
	v_mfma_f32_16x16x32_bf16 v[88:91], v[194:197], v[158:161], v[88:91]
	v_mfma_f32_16x16x32_bf16 v[84:87], v[198:201], v[158:161], v[84:87]
	v_mfma_f32_16x16x32_bf16 v[80:83], v[218:221], v[158:161], v[80:83]
	s_setprio 0
	ds_read_b128 v[230:233], v137 offset:15360
	s_waitcnt lgkmcnt(4)
	s_setprio 1
	v_mfma_f32_16x16x32_bf16 v[76:79], v[186:189], v[138:141], v[76:79]
	v_mfma_f32_16x16x32_bf16 v[72:75], v[194:197], v[138:141], v[72:75]
	v_mfma_f32_16x16x32_bf16 v[68:71], v[198:201], v[138:141], v[68:71]
	v_mfma_f32_16x16x32_bf16 v[64:67], v[218:221], v[138:141], v[64:67]
	s_waitcnt lgkmcnt(0)
	s_setprio 0
	s_waitcnt vmcnt(0)
	s_add_i32 s1, s1, 64
	s_add_i32 s17, s17, 0x10000
	s_add_i32 s18, s18, 1
	s_cmpk_lg_i32 s1, 0x100
	s_waitcnt vmcnt(0)
	s_barrier
	s_cbranch_scc1 .LBB0_819
	v_mfma_f32_16x16x32_bf16 v[60:63], v[186:189], v[190:193], v[60:63]
	v_mfma_f32_16x16x32_bf16 v[56:59], v[194:197], v[190:193], v[56:59]
	v_mfma_f32_16x16x32_bf16 v[52:55], v[198:201], v[190:193], v[52:55]
	v_mfma_f32_16x16x32_bf16 v[48:51], v[218:221], v[190:193], v[48:51]
	v_mfma_f32_16x16x32_bf16 v[44:47], v[186:189], v[222:225], v[44:47]
	v_mfma_f32_16x16x32_bf16 v[40:43], v[194:197], v[222:225], v[40:43]
	v_mfma_f32_16x16x32_bf16 v[36:39], v[198:201], v[222:225], v[36:39]
	v_mfma_f32_16x16x32_bf16 v[32:35], v[218:221], v[222:225], v[32:35]
	v_mfma_f32_16x16x32_bf16 v[28:31], v[186:189], v[226:229], v[28:31]
	v_mfma_f32_16x16x32_bf16 v[24:27], v[194:197], v[226:229], v[24:27]
	v_mfma_f32_16x16x32_bf16 v[20:23], v[198:201], v[226:229], v[20:23]
	v_mfma_f32_16x16x32_bf16 v[16:19], v[218:221], v[226:229], v[16:19]
	v_mfma_f32_16x16x32_bf16 v[8:11], v[186:189], v[230:233], v[8:11]
	v_mfma_f32_16x16x32_bf16 v[4:7], v[194:197], v[230:233], v[4:7]
	v_mfma_f32_16x16x32_bf16 v[0:3], v[198:201], v[230:233], v[0:3]
	v_mfma_f32_16x16x32_bf16 v[12:15], v[218:221], v[230:233], v[12:15]
	s_nop 7
	s_nop 1

; #define LDB_(dst, ks) _Pragma("unroll") for (int n = 0; n < 4; ++n) dst[n] = *(const bf16x8*)(sB + b_off + n * 2048 + (ks) * 1024)
; #define LDA_(dst, ks, h) _Pragma("unroll") for (int m = 0; m < 4; ++m) dst[m] = *(const bf16x8*)(sA + a_off + ((h) * 4 + m) * 2048 + (ks) * 1024)
; #define MMA_(A, B, h) _Pragma("unroll") for (int m = 0; m < 4; ++m) _Pragma("unroll") for (int n = 0; n < 4; ++n) \
;       acc[(h) * 4 + m][n] = SWAP ? MFMA16(B[n], A[m], acc[(h) * 4 + m][n]) : MFMA16(A[m], B[n], acc[(h) * 4 + m][n])
; template <int MF, int NF, bool SWAP = true>
; DI void gemm_main(f32x4 (&acc)[MF][NF], const u16* __restrict__ Ab, int lda, const u16* __restrict__ Bb, int ldb,
;                   int K, char* shm) {
;     ...
;     if constexpr (MF == 8 && NF == 4) {
;       bf16x8 B0[4], B1[4], A0[4], A1[4], A2[4], A3[4];
;     ...
;       LDB_(B0, 0); LDA_(A0, 0, 0);
;       LDA_(A1, 0, 1); MMA_(A0, B0, 0);
;       LDB_(B1, 1); LDA_(A2, 1, 0); MMA_(A1, B0, 1);
;       LDA_(A3, 1, 1); MMA_(A2, B1, 0);
;       MMA_(A3, B1, 1);
;     ...
;       __builtin_amdgcn_sched_group_barrier(0x100, 8, 0);
; #pragma unroll
;       for (int i = 0; i < 4; ++i) { __builtin_amdgcn_sched_group_barrier(0x100, 1, 0); __builtin_amdgcn_sched_group_barrier(0x008, 4, 0); }
; #pragma unroll
;       for (int i = 0; i < 8; ++i) { __builtin_amdgcn_sched_group_barrier(0x100, 1, 0); __builtin_amdgcn_sched_group_barrier(0x008, 2, 0); }
; #pragma unroll
;       for (int i = 0; i < 4; ++i) { __builtin_amdgcn_sched_group_barrier(0x100, 1, 0); __builtin_amdgcn_sched_group_barrier(0x008, 4, 0); }
;       __builtin_amdgcn_sched_group_barrier(0x008, 16, 0);
;       __builtin_amdgcn_sched_barrier(0);
;     ...
;     } else {
;       asm volatile("s_waitcnt vmcnt(0)" ::: "memory");
;       __syncthreads();
;     }
.Lg_rot874_main:
	s_waitcnt lgkmcnt(4)
	s_setprio 1
	v_mfma_f32_16x16x32_bf16 v[124:127], v[154:157], v[170:173], v[124:127]
	v_mfma_f32_16x16x32_bf16 v[120:123], v[158:161], v[170:173], v[120:123]
	v_mfma_f32_16x16x32_bf16 v[116:119], v[162:165], v[170:173], v[116:119]
	v_mfma_f32_16x16x32_bf16 v[112:115], v[166:169], v[170:173], v[112:115]
	s_setprio 0
	ds_read_b128 v[170:173], v153 offset:10240
	s_waitcnt lgkmcnt(4)
	s_setprio 1
	v_mfma_f32_16x16x32_bf16 v[108:111], v[154:157], v[174:177], v[108:111]
	v_mfma_f32_16x16x32_bf16 v[104:107], v[158:161], v[174:177], v[104:107]
	v_mfma_f32_16x16x32_bf16 v[100:103], v[162:165], v[174:177], v[100:103]
	v_mfma_f32_16x16x32_bf16 v[96:99], v[166:169], v[174:177], v[96:99]
	s_setprio 0
	ds_read_b128 v[174:177], v153 offset:12288
	s_waitcnt lgkmcnt(4)
	s_setprio 1
	v_mfma_f32_16x16x32_bf16 v[92:95], v[154:157], v[178:181], v[92:95]
	v_mfma_f32_16x16x32_bf16 v[88:91], v[158:161], v[178:181], v[88:91]
	v_mfma_f32_16x16x32_bf16 v[84:87], v[162:165], v[178:181], v[84:87]
	v_mfma_f32_16x16x32_bf16 v[80:83], v[166:169], v[178:181], v[80:83]
	s_setprio 0
	ds_read_b128 v[178:181], v153 offset:14336
	s_waitcnt lgkmcnt(4)
	s_setprio 1
	v_mfma_f32_16x16x32_bf16 v[76:79], v[154:157], v[182:185], v[76:79]
	v_mfma_f32_16x16x32_bf16 v[72:75], v[158:161], v[182:185], v[72:75]
	v_mfma_f32_16x16x32_bf16 v[68:71], v[162:165], v[182:185], v[68:71]
	v_mfma_f32_16x16x32_bf16 v[64:67], v[166:169], v[182:185], v[64:67]
	s_setprio 0
	ds_read_b128 v[218:221], v194 offset:33792
	s_waitcnt lgkmcnt(4)
	s_setprio 1
	v_mfma_f32_16x16x32_bf16 v[60:63], v[154:157], v[186:189], v[60:63]
	v_mfma_f32_16x16x32_bf16 v[56:59], v[158:161], v[186:189], v[56:59]
	s_setprio 0
	ds_read_b128 v[226:229], v194 offset:35840
	s_setprio 1
	v_mfma_f32_16x16x32_bf16 v[52:55], v[162:165], v[186:189], v[52:55]
	v_mfma_f32_16x16x32_bf16 v[48:51], v[166:169], v[186:189], v[48:51]
	s_setprio 0
	ds_read_b128 v[230:233], v194 offset:37888
	s_waitcnt lgkmcnt(5)
	s_setprio 1
	v_mfma_f32_16x16x32_bf16 v[44:47], v[154:157], v[170:173], v[44:47]
	v_mfma_f32_16x16x32_bf16 v[40:43], v[158:161], v[170:173], v[40:43]
	s_setprio 0
	ds_read_b128 v[234:237], v194 offset:39936
	s_setprio 1
	v_mfma_f32_16x16x32_bf16 v[36:39], v[162:165], v[170:173], v[36:39]
	v_mfma_f32_16x16x32_bf16 v[32:35], v[166:169], v[170:173], v[32:35]
	s_setprio 0
	ds_read_b128 v[170:173], v153 offset:1024
	s_waitcnt lgkmcnt(6)
	s_setprio 1
	v_mfma_f32_16x16x32_bf16 v[28:31], v[154:157], v[174:177], v[28:31]
	v_mfma_f32_16x16x32_bf16 v[24:27], v[158:161], v[174:177], v[24:27]
	s_setprio 0
	ds_read_b128 v[198:201], v153 offset:3072
	s_setprio 1
	v_mfma_f32_16x16x32_bf16 v[16:19], v[162:165], v[174:177], v[16:19]
	v_mfma_f32_16x16x32_bf16 v[12:15], v[166:169], v[174:177], v[12:15]
	s_setprio 0
	ds_read_b128 v[174:177], v153 offset:5120
	s_waitcnt lgkmcnt(7)
	s_setprio 1
	v_mfma_f32_16x16x32_bf16 v[8:11], v[154:157], v[178:181], v[8:11]
	v_mfma_f32_16x16x32_bf16 v[4:7], v[158:161], v[178:181], v[4:7]
	s_setprio 0
	ds_read_b128 v[154:157], v153 offset:7168
	s_setprio 1
	v_mfma_f32_16x16x32_bf16 v[0:3], v[162:165], v[178:181], v[0:3]
	v_mfma_f32_16x16x32_bf16 v[20:23], v[166:169], v[178:181], v[20:23]
	s_setprio 0
	ds_read_b128 v[222:225], v153 offset:9216
	s_waitcnt lgkmcnt(4)
	s_setprio 1
	v_mfma_f32_16x16x32_bf16 v[124:127], v[218:221], v[170:173], v[124:127]
	v_mfma_f32_16x16x32_bf16 v[120:123], v[226:229], v[170:173], v[120:123]
	v_mfma_f32_16x16x32_bf16 v[116:119], v[230:233], v[170:173], v[116:119]
	v_mfma_f32_16x16x32_bf16 v[112:115], v[234:237], v[170:173], v[112:115]
	s_setprio 0
	ds_read_b128 v[238:241], v153 offset:11264
	s_waitcnt lgkmcnt(4)
	s_setprio 1
	v_mfma_f32_16x16x32_bf16 v[108:111], v[218:221], v[198:201], v[108:111]
	v_mfma_f32_16x16x32_bf16 v[104:107], v[226:229], v[198:201], v[104:107]
	v_mfma_f32_16x16x32_bf16 v[100:103], v[230:233], v[198:201], v[100:103]
	v_mfma_f32_16x16x32_bf16 v[96:99], v[234:237], v[198:201], v[96:99]
	s_setprio 0
	ds_read_b128 v[242:245], v153 offset:13312
	s_waitcnt lgkmcnt(4)
	s_setprio 1
	v_mfma_f32_16x16x32_bf16 v[92:95], v[218:221], v[174:177], v[92:95]
	v_mfma_f32_16x16x32_bf16 v[88:91], v[226:229], v[174:177], v[88:91]
	v_mfma_f32_16x16x32_bf16 v[84:87], v[230:233], v[174:177], v[84:87]
	v_mfma_f32_16x16x32_bf16 v[80:83], v[234:237], v[174:177], v[80:83]
	s_setprio 0
	ds_read_b128 v[246:249], v153 offset:15360
	s_waitcnt lgkmcnt(4)
	s_setprio 1
	v_mfma_f32_16x16x32_bf16 v[76:79], v[218:221], v[154:157], v[76:79]
	v_mfma_f32_16x16x32_bf16 v[72:75], v[226:229], v[154:157], v[72:75]
	v_mfma_f32_16x16x32_bf16 v[68:71], v[230:233], v[154:157], v[68:71]
	v_mfma_f32_16x16x32_bf16 v[64:67], v[234:237], v[154:157], v[64:67]
	s_waitcnt lgkmcnt(0)
	s_setprio 0
	s_waitcnt vmcnt(0)
	s_add_i32 s11, s11, 64
	s_add_i32 s21, s21, 0x10000
	s_add_i32 s22, s22, 1
	s_cmpk_lg_i32 s11, 0x400
	s_waitcnt vmcnt(0)
	s_barrier
	s_cbranch_scc1 .LBB0_874
	v_mfma_f32_16x16x32_bf16 v[60:63], v[218:221], v[222:225], v[60:63]
	v_mfma_f32_16x16x32_bf16 v[56:59], v[226:229], v[222:225], v[56:59]
	v_mfma_f32_16x16x32_bf16 v[52:55], v[230:233], v[222:225], v[52:55]
	v_mfma_f32_16x16x32_bf16 v[48:51], v[234:237], v[222:225], v[48:51]
	v_mfma_f32_16x16x32_bf16 v[44:47], v[218:221], v[238:241], v[44:47]
	v_mfma_f32_16x16x32_bf16 v[40:43], v[226:229], v[238:241], v[40:43]
	v_mfma_f32_16x16x32_bf16 v[36:39], v[230:233], v[238:241], v[36:39]
	v_mfma_f32_16x16x32_bf16 v[32:35], v[234:237], v[238:241], v[32:35]
	v_mfma_f32_16x16x32_bf16 v[28:31], v[218:221], v[242:245], v[28:31]
	v_mfma_f32_16x16x32_bf16 v[24:27], v[226:229], v[242:245], v[24:27]
	v_mfma_f32_16x16x32_bf16 v[16:19], v[230:233], v[242:245], v[16:19]
	v_mfma_f32_16x16x32_bf16 v[12:15], v[234:237], v[242:245], v[12:15]
	v_mfma_f32_16x16x32_bf16 v[8:11], v[218:221], v[246:249], v[8:11]
	v_mfma_f32_16x16x32_bf16 v[4:7], v[226:229], v[246:249], v[4:7]
	v_mfma_f32_16x16x32_bf16 v[0:3], v[230:233], v[246:249], v[0:3]
	v_mfma_f32_16x16x32_bf16 v[20:23], v[234:237], v[246:249], v[20:23]
	s_nop 7
	s_nop 1
